# speedup vs baseline: 1.0091x; 1.0056x over previous
; __device__ __forceinline__ void wkv_phase(const WkvT& W, unsigned char* lds) {
;     ...
;                 const float* pp = sP + bo + jj * 12;
;                 const float* pv = sV + bi * 512 + il;
;                 f32x4 nA = *(const f32x4*)pp, nB = *(const f32x4*)(pp + 4); f32x2 nr = *(const f32x2*)(pp + 8); float nv = pv[0];
;                 float yk0 = 0.f, yk1 = 0.f, ep = 0.f;
;                 const bool oddrow = (lane & 16) != 0;
; #pragma unroll
;                 for (int t = 0; t < 32; ++t) {
;                     const f32x2 a2 = {nA[0], nA[1]}, w2 = {nA[2], nA[3]}, b2 = {nB[0], nB[1]}, k2 = {nB[2], nB[3]}, r2 = nr; const float v = nv;
;                     if (t + 1 < 32) { nA = *(const f32x4*)(pp + (t + 1) * 384); nB = *(const f32x4*)(pp + (t + 1) * 384 + 4); nr = *(const f32x2*)(pp + (t + 1) * 384 + 8); nv = pv[(t + 1) * 16]; }
;                     float S0 = S.x, S1 = S.y;
;                     float d = S0 * a2.x; d = __builtin_fmaf(S1, a2.y, d);
;                     float t0 = S0 * w2.x; t0 = __builtin_fmaf(v, k2.x, t0); asm volatile("" : "+v"(t0));
;                     float t1 = S1 * w2.y; t1 = __builtin_fmaf(v, k2.y, t1); asm volatile("" : "+v"(t1));
;                     float yprev; const float sa = wkv_reduce(d, ep, yprev);
;                     S0 = __builtin_fmaf(sa, b2.x, t0); asm volatile("" : "+v"(S0));
;                     S1 = __builtin_fmaf(sa, b2.y, t1); asm volatile("" : "+v"(S1));
;                     ep = S0 * r2.x; ep = __builtin_fmaf(S1, r2.y, ep);
;                     S.x = S0; S.y = S1;
;                     if (t >= 1) { const bool hit = oddrow && ((lane & 15) == ((t - 1) & 15)); if (t <= 16) yk0 = hit ? yprev : yk0; else yk1 = hit ? yprev : yk1; }
;                 }
.Lwkv4_b1_entry:
	s_bitcmp1_b32 s99, 8
	s_cbranch_scc1 .Lwkv4_b1_skip
	ds_read_b128 v[190:193], v182
	ds_read_b128 v[194:197], v182 offset:32
	ds_read_b128 v[198:201], v183
	ds_read_b128 v[202:205], v183 offset:32
	ds_read_b128 v[228:231], v155
	ds_read2_b32 v[240:241], v186 offset0:0 offset1:16
	ds_read_b128 v[206:209], v182 offset:1536
	ds_read_b128 v[210:213], v182 offset:1568
	ds_read_b128 v[214:217], v183 offset:1536
	ds_read_b128 v[218:221], v183 offset:1568
	ds_read_b128 v[232:235], v155 offset:1536
	s_waitcnt lgkmcnt(5)
	v_pk_mul_f32 v[150:151], v[142:143], v[190:191]
	v_pk_fma_f32 v[150:151], v[144:145], v[198:199], v[150:151]
	v_pk_mul_f32 v[146:147], v[142:143], v[192:193]
	v_add_f32_e32 v154, v150, v151
	v_pk_mul_f32 v[148:149], v[144:145], v[200:201]
	v_pk_fma_f32 v[146:147], v[240:241], v[196:197], v[146:147] op_sel:[0,0,0] op_sel_hi:[0,1,1]
	v_add_f32_dpp v154, v154, v154 quad_perm:[1,0,3,2] row_mask:0xf bank_mask:0xf bound_ctrl:1
	v_pk_fma_f32 v[148:149], v[240:241], v[204:205], v[148:149] op_sel:[0,0,0] op_sel_hi:[0,1,1]
	s_nop 0
	v_add_f32_dpp v154, v154, v154 quad_perm:[2,3,0,1] row_mask:0xf bank_mask:0xf bound_ctrl:1
	ds_read_b128 v[126:129], v182 offset:3072
	ds_read_b128 v[130:133], v182 offset:3104
	v_add_f32_dpp v154, v154, v154 row_half_mirror row_mask:0xf bank_mask:0xf bound_ctrl:1
	ds_read_b128 v[134:137], v183 offset:3072
	ds_read_b128 v[222:225], v183 offset:3104
	v_add_f32_dpp v154, v154, v154 row_mirror row_mask:0xf bank_mask:0xf bound_ctrl:1
	v_pk_fma_f32 v[146:147], v[154:155], v[194:195], v[146:147] op_sel_hi:[0,1,1]
	v_pk_fma_f32 v[148:149], v[154:155], v[202:203], v[148:149] op_sel_hi:[0,1,1]
	ds_read_b128 v[236:239], v155 offset:3072
	ds_read2_b32 v[242:243], v186 offset0:32 offset1:48
	s_waitcnt lgkmcnt(6)
	v_pk_mul_f32 v[150:151], v[146:147], v[206:207]
	v_pk_fma_f32 v[150:151], v[148:149], v[214:215], v[150:151]
	v_pk_mul_f32 v[152:153], v[146:147], v[228:229]
	v_add_f32_e32 v154, v150, v151
	v_pk_fma_f32 v[152:153], v[148:149], v[230:231], v[152:153]
	v_pk_mul_f32 v[142:143], v[146:147], v[208:209]
	v_add_f32_dpp v154, v154, v154 quad_perm:[1,0,3,2] row_mask:0xf bank_mask:0xf bound_ctrl:1
	v_pk_mul_f32 v[144:145], v[148:149], v[216:217]
	v_add_f32_e32 v156, v152, v153
	v_add_f32_dpp v154, v154, v154 quad_perm:[2,3,0,1] row_mask:0xf bank_mask:0xf bound_ctrl:1
	v_pk_fma_f32 v[142:143], v[240:241], v[212:213], v[142:143] op_sel:[1,0,0] op_sel_hi:[1,1,1]
	v_pk_fma_f32 v[144:145], v[240:241], v[220:221], v[144:145] op_sel:[1,0,0] op_sel_hi:[1,1,1]
	v_add_f32_dpp v154, v154, v154 row_half_mirror row_mask:0xf bank_mask:0xf bound_ctrl:1
	ds_read_b128 v[190:193], v182 offset:4608
	ds_read_b128 v[194:197], v182 offset:4640
	v_add_f32_dpp v154, v154, v154 row_mirror row_mask:0xf bank_mask:0xf bound_ctrl:1
	v_pk_fma_f32 v[142:143], v[154:155], v[210:211], v[142:143] op_sel_hi:[0,1,1]
	v_pk_fma_f32 v[144:145], v[154:155], v[218:219], v[144:145] op_sel_hi:[0,1,1]
	ds_read_b128 v[198:201], v183 offset:4608
	ds_read_b128 v[202:205], v183 offset:4640
	ds_read_b128 v[228:231], v155 offset:4608
	s_waitcnt lgkmcnt(5)
	v_pk_mul_f32 v[150:151], v[142:143], v[126:127]
	v_pk_fma_f32 v[150:151], v[144:145], v[134:135], v[150:151]
	v_pk_mul_f32 v[152:153], v[142:143], v[232:233]
	v_add_f32_e32 v154, v150, v151
	v_pk_fma_f32 v[152:153], v[144:145], v[234:235], v[152:153]
	v_pk_mul_f32 v[146:147], v[142:143], v[128:129]
	v_add_f32_dpp v154, v154, v154 quad_perm:[1,0,3,2] row_mask:0xf bank_mask:0xf bound_ctrl:1
	v_pk_mul_f32 v[148:149], v[144:145], v[136:137]
	v_add_f32_e32 v157, v152, v153
	v_add_f32_dpp v154, v154, v154 quad_perm:[2,3,0,1] row_mask:0xf bank_mask:0xf bound_ctrl:1
	v_pk_fma_f32 v[146:147], v[242:243], v[132:133], v[146:147] op_sel:[0,0,0] op_sel_hi:[0,1,1]
	v_pk_fma_f32 v[148:149], v[242:243], v[224:225], v[148:149] op_sel:[0,0,0] op_sel_hi:[0,1,1]
	v_add_f32_dpp v154, v154, v154 row_half_mirror row_mask:0xf bank_mask:0xf bound_ctrl:1
	ds_read_b128 v[206:209], v182 offset:6144
	ds_read_b128 v[210:213], v182 offset:6176
	v_add_f32_dpp v154, v154, v154 row_mirror row_mask:0xf bank_mask:0xf bound_ctrl:1
	ds_read_b128 v[214:217], v183 offset:6144
	v_pk_fma_f32 v[146:147], v[154:155], v[130:131], v[146:147] op_sel_hi:[0,1,1]
	v_pk_fma_f32 v[148:149], v[154:155], v[222:223], v[148:149] op_sel_hi:[0,1,1]
	ds_read_b128 v[218:221], v183 offset:6176
	ds_read_b128 v[232:235], v155 offset:6144
	ds_read2_b32 v[240:241], v186 offset0:64 offset1:80
	s_waitcnt lgkmcnt(6)
	v_pk_mul_f32 v[150:151], v[146:147], v[190:191]
	v_pk_fma_f32 v[150:151], v[148:149], v[198:199], v[150:151]
	v_pk_mul_f32 v[152:153], v[146:147], v[236:237]
	v_add_f32_e32 v154, v150, v151
	v_pk_fma_f32 v[152:153], v[148:149], v[238:239], v[152:153]
	v_pk_mul_f32 v[142:143], v[146:147], v[192:193]
	v_add_f32_dpp v154, v154, v154 quad_perm:[1,0,3,2] row_mask:0xf bank_mask:0xf bound_ctrl:1
	v_pk_mul_f32 v[144:145], v[148:149], v[200:201]
	v_add_f32_e32 v158, v152, v153
	v_add_f32_dpp v154, v154, v154 quad_perm:[2,3,0,1] row_mask:0xf bank_mask:0xf bound_ctrl:1
	v_pk_fma_f32 v[142:143], v[242:243], v[196:197], v[142:143] op_sel:[1,0,0] op_sel_hi:[1,1,1]
	v_pk_fma_f32 v[144:145], v[242:243], v[204:205], v[144:145] op_sel:[1,0,0] op_sel_hi:[1,1,1]
	v_add_f32_dpp v154, v154, v154 row_half_mirror row_mask:0xf bank_mask:0xf bound_ctrl:1
	ds_read_b128 v[126:129], v182 offset:7680
	ds_read_b128 v[130:133], v182 offset:7712
	v_add_f32_dpp v154, v154, v154 row_mirror row_mask:0xf bank_mask:0xf bound_ctrl:1
	v_pk_fma_f32 v[142:143], v[154:155], v[194:195], v[142:143] op_sel_hi:[0,1,1]
	v_pk_fma_f32 v[144:145], v[154:155], v[202:203], v[144:145] op_sel_hi:[0,1,1]
	ds_read_b128 v[134:137], v183 offset:7680
	ds_read_b128 v[222:225], v183 offset:7712
	ds_read_b128 v[236:239], v155 offset:7680
	s_waitcnt lgkmcnt(5)
; __device__ __forceinline__ void wkv_phase(const WkvT& W, unsigned char* lds) {
;     ...
;                 for (int t = 0; t < 32; ++t) {
;                     const f32x2 a2 = {nA[0], nA[1]}, w2 = {nA[2], nA[3]}, b2 = {nB[0], nB[1]}, k2 = {nB[2], nB[3]}, r2 = nr; const float v = nv;
;                     if (t + 1 < 32) { nA = *(const f32x4*)(pp + (t + 1) * 384); nB = *(const f32x4*)(pp + (t + 1) * 384 + 4); nr = *(const f32x2*)(pp + (t + 1) * 384 + 8); nv = pv[(t + 1) * 16]; }
;                     float S0 = S.x, S1 = S.y;
;                     float d = S0 * a2.x; d = __builtin_fmaf(S1, a2.y, d);
;                     float t0 = S0 * w2.x; t0 = __builtin_fmaf(v, k2.x, t0); asm volatile("" : "+v"(t0));
;                     float t1 = S1 * w2.y; t1 = __builtin_fmaf(v, k2.y, t1); asm volatile("" : "+v"(t1));
;                     float yprev; const float sa = wkv_reduce(d, ep, yprev);
;                     S0 = __builtin_fmaf(sa, b2.x, t0); asm volatile("" : "+v"(S0));
;                     S1 = __builtin_fmaf(sa, b2.y, t1); asm volatile("" : "+v"(S1));
;                     ep = S0 * r2.x; ep = __builtin_fmaf(S1, r2.y, ep);
;                     S.x = S0; S.y = S1;
;                     if (t >= 1) { const bool hit = oddrow && ((lane & 15) == ((t - 1) & 15)); if (t <= 16) yk0 = hit ? yprev : yk0; else yk1 = hit ? yprev : yk1; }
;                 }
	v_pk_mul_f32 v[150:151], v[142:143], v[206:207]
	v_pk_fma_f32 v[150:151], v[144:145], v[214:215], v[150:151]
	v_pk_mul_f32 v[152:153], v[142:143], v[228:229]
	v_add_f32_e32 v154, v150, v151
	v_pk_fma_f32 v[152:153], v[144:145], v[230:231], v[152:153]
	v_pk_mul_f32 v[146:147], v[142:143], v[208:209]
	v_add_f32_dpp v154, v154, v154 quad_perm:[1,0,3,2] row_mask:0xf bank_mask:0xf bound_ctrl:1
	v_pk_mul_f32 v[148:149], v[144:145], v[216:217]
	v_add_f32_e32 v159, v152, v153
	v_add_f32_dpp v154, v154, v154 quad_perm:[2,3,0,1] row_mask:0xf bank_mask:0xf bound_ctrl:1
	v_pk_fma_f32 v[146:147], v[240:241], v[212:213], v[146:147] op_sel:[0,0,0] op_sel_hi:[0,1,1]
	v_pk_fma_f32 v[148:149], v[240:241], v[220:221], v[148:149] op_sel:[0,0,0] op_sel_hi:[0,1,1]
	v_add_f32_dpp v154, v154, v154 row_half_mirror row_mask:0xf bank_mask:0xf bound_ctrl:1
	ds_read_b128 v[190:193], v182 offset:9216
	ds_read_b128 v[194:197], v182 offset:9248
	v_add_f32_dpp v154, v154, v154 row_mirror row_mask:0xf bank_mask:0xf bound_ctrl:1
	ds_read_b128 v[198:201], v183 offset:9216
	v_pk_fma_f32 v[146:147], v[154:155], v[210:211], v[146:147] op_sel_hi:[0,1,1]
	v_pk_fma_f32 v[148:149], v[154:155], v[218:219], v[148:149] op_sel_hi:[0,1,1]
	ds_read_b128 v[202:205], v183 offset:9248
	ds_read_b128 v[228:231], v155 offset:9216
	ds_read2_b32 v[242:243], v186 offset0:96 offset1:112
	s_waitcnt lgkmcnt(6)
	v_pk_mul_f32 v[150:151], v[146:147], v[126:127]
	v_pk_fma_f32 v[150:151], v[148:149], v[134:135], v[150:151]
	v_pk_mul_f32 v[152:153], v[146:147], v[232:233]
	v_add_f32_e32 v154, v150, v151
	v_pk_fma_f32 v[152:153], v[148:149], v[234:235], v[152:153]
	v_pk_mul_f32 v[142:143], v[146:147], v[128:129]
	v_add_f32_dpp v154, v154, v154 quad_perm:[1,0,3,2] row_mask:0xf bank_mask:0xf bound_ctrl:1
	v_pk_mul_f32 v[144:145], v[148:149], v[136:137]
	v_add_f32_e32 v160, v152, v153
	v_add_f32_dpp v154, v154, v154 quad_perm:[2,3,0,1] row_mask:0xf bank_mask:0xf bound_ctrl:1
	v_pk_fma_f32 v[142:143], v[240:241], v[132:133], v[142:143] op_sel:[1,0,0] op_sel_hi:[1,1,1]
	v_pk_fma_f32 v[144:145], v[240:241], v[224:225], v[144:145] op_sel:[1,0,0] op_sel_hi:[1,1,1]
	v_add_f32_dpp v154, v154, v154 row_half_mirror row_mask:0xf bank_mask:0xf bound_ctrl:1
	ds_read_b128 v[206:209], v182 offset:10752
	ds_read_b128 v[210:213], v182 offset:10784
	v_add_f32_dpp v154, v154, v154 row_mirror row_mask:0xf bank_mask:0xf bound_ctrl:1
	v_pk_fma_f32 v[142:143], v[154:155], v[130:131], v[142:143] op_sel_hi:[0,1,1]
	v_pk_fma_f32 v[144:145], v[154:155], v[222:223], v[144:145] op_sel_hi:[0,1,1]
	ds_read_b128 v[214:217], v183 offset:10752
	ds_read_b128 v[218:221], v183 offset:10784
	ds_read_b128 v[232:235], v155 offset:10752
	s_waitcnt lgkmcnt(5)
	v_pk_mul_f32 v[150:151], v[142:143], v[190:191]
	v_pk_fma_f32 v[150:151], v[144:145], v[198:199], v[150:151]
	v_pk_mul_f32 v[152:153], v[142:143], v[236:237]
	v_add_f32_e32 v154, v150, v151
	v_pk_fma_f32 v[152:153], v[144:145], v[238:239], v[152:153]
	v_pk_mul_f32 v[146:147], v[142:143], v[192:193]
	v_add_f32_dpp v154, v154, v154 quad_perm:[1,0,3,2] row_mask:0xf bank_mask:0xf bound_ctrl:1
	v_pk_mul_f32 v[148:149], v[144:145], v[200:201]
	v_add_f32_e32 v161, v152, v153
	v_add_f32_dpp v154, v154, v154 quad_perm:[2,3,0,1] row_mask:0xf bank_mask:0xf bound_ctrl:1
	v_pk_fma_f32 v[146:147], v[242:243], v[196:197], v[146:147] op_sel:[0,0,0] op_sel_hi:[0,1,1]
	v_pk_fma_f32 v[148:149], v[242:243], v[204:205], v[148:149] op_sel:[0,0,0] op_sel_hi:[0,1,1]
	v_add_f32_dpp v154, v154, v154 row_half_mirror row_mask:0xf bank_mask:0xf bound_ctrl:1
	ds_read_b128 v[126:129], v182 offset:12288
	ds_read_b128 v[130:133], v182 offset:12320
	v_add_f32_dpp v154, v154, v154 row_mirror row_mask:0xf bank_mask:0xf bound_ctrl:1
	ds_read_b128 v[134:137], v183 offset:12288
	v_pk_fma_f32 v[146:147], v[154:155], v[194:195], v[146:147] op_sel_hi:[0,1,1]
	v_pk_fma_f32 v[148:149], v[154:155], v[202:203], v[148:149] op_sel_hi:[0,1,1]
	ds_read_b128 v[222:225], v183 offset:12320
	ds_read_b128 v[236:239], v155 offset:12288
	ds_read2_b32 v[240:241], v186 offset0:128 offset1:144
	s_waitcnt lgkmcnt(6)
	v_pk_mul_f32 v[150:151], v[146:147], v[206:207]
	v_pk_fma_f32 v[150:151], v[148:149], v[214:215], v[150:151]
	v_pk_mul_f32 v[152:153], v[146:147], v[228:229]
	v_add_f32_e32 v154, v150, v151
	v_pk_fma_f32 v[152:153], v[148:149], v[230:231], v[152:153]
	v_pk_mul_f32 v[142:143], v[146:147], v[208:209]
	v_add_f32_dpp v154, v154, v154 quad_perm:[1,0,3,2] row_mask:0xf bank_mask:0xf bound_ctrl:1
	v_pk_mul_f32 v[144:145], v[148:149], v[216:217]
	v_add_f32_e32 v162, v152, v153
	v_add_f32_dpp v154, v154, v154 quad_perm:[2,3,0,1] row_mask:0xf bank_mask:0xf bound_ctrl:1
	v_pk_fma_f32 v[142:143], v[242:243], v[212:213], v[142:143] op_sel:[1,0,0] op_sel_hi:[1,1,1]
	v_pk_fma_f32 v[144:145], v[242:243], v[220:221], v[144:145] op_sel:[1,0,0] op_sel_hi:[1,1,1]
	v_add_f32_dpp v154, v154, v154 row_half_mirror row_mask:0xf bank_mask:0xf bound_ctrl:1
	ds_read_b128 v[190:193], v182 offset:13824
	ds_read_b128 v[194:197], v182 offset:13856
	v_add_f32_dpp v154, v154, v154 row_mirror row_mask:0xf bank_mask:0xf bound_ctrl:1
	v_pk_fma_f32 v[142:143], v[154:155], v[210:211], v[142:143] op_sel_hi:[0,1,1]
	v_pk_fma_f32 v[144:145], v[154:155], v[218:219], v[144:145] op_sel_hi:[0,1,1]
	ds_read_b128 v[198:201], v183 offset:13824
	ds_read_b128 v[202:205], v183 offset:13856
	ds_read_b128 v[228:231], v155 offset:13824
	s_waitcnt lgkmcnt(5)
; __device__ __forceinline__ void wkv_phase(const WkvT& W, unsigned char* lds) {
;     ...
;                 for (int t = 0; t < 32; ++t) {
;                     const f32x2 a2 = {nA[0], nA[1]}, w2 = {nA[2], nA[3]}, b2 = {nB[0], nB[1]}, k2 = {nB[2], nB[3]}, r2 = nr; const float v = nv;
;                     if (t + 1 < 32) { nA = *(const f32x4*)(pp + (t + 1) * 384); nB = *(const f32x4*)(pp + (t + 1) * 384 + 4); nr = *(const f32x2*)(pp + (t + 1) * 384 + 8); nv = pv[(t + 1) * 16]; }
;                     float S0 = S.x, S1 = S.y;
;                     float d = S0 * a2.x; d = __builtin_fmaf(S1, a2.y, d);
;                     float t0 = S0 * w2.x; t0 = __builtin_fmaf(v, k2.x, t0); asm volatile("" : "+v"(t0));
;                     float t1 = S1 * w2.y; t1 = __builtin_fmaf(v, k2.y, t1); asm volatile("" : "+v"(t1));
;                     float yprev; const float sa = wkv_reduce(d, ep, yprev);
;                     S0 = __builtin_fmaf(sa, b2.x, t0); asm volatile("" : "+v"(S0));
;                     S1 = __builtin_fmaf(sa, b2.y, t1); asm volatile("" : "+v"(S1));
;                     ep = S0 * r2.x; ep = __builtin_fmaf(S1, r2.y, ep);
;                     S.x = S0; S.y = S1;
;                     if (t >= 1) { const bool hit = oddrow && ((lane & 15) == ((t - 1) & 15)); if (t <= 16) yk0 = hit ? yprev : yk0; else yk1 = hit ? yprev : yk1; }
;                 }
	v_pk_mul_f32 v[150:151], v[142:143], v[126:127]
	v_pk_fma_f32 v[150:151], v[144:145], v[134:135], v[150:151]
	v_pk_mul_f32 v[152:153], v[142:143], v[232:233]
	v_add_f32_e32 v154, v150, v151
	v_pk_fma_f32 v[152:153], v[144:145], v[234:235], v[152:153]
	v_pk_mul_f32 v[146:147], v[142:143], v[128:129]
	v_add_f32_dpp v154, v154, v154 quad_perm:[1,0,3,2] row_mask:0xf bank_mask:0xf bound_ctrl:1
	v_pk_mul_f32 v[148:149], v[144:145], v[136:137]
	v_add_f32_e32 v163, v152, v153
	v_add_f32_dpp v154, v154, v154 quad_perm:[2,3,0,1] row_mask:0xf bank_mask:0xf bound_ctrl:1
	v_pk_fma_f32 v[146:147], v[240:241], v[132:133], v[146:147] op_sel:[0,0,0] op_sel_hi:[0,1,1]
	v_pk_fma_f32 v[148:149], v[240:241], v[224:225], v[148:149] op_sel:[0,0,0] op_sel_hi:[0,1,1]
	v_add_f32_dpp v154, v154, v154 row_half_mirror row_mask:0xf bank_mask:0xf bound_ctrl:1
	ds_read_b128 v[206:209], v182 offset:15360
	ds_read_b128 v[210:213], v182 offset:15392
	v_add_f32_dpp v154, v154, v154 row_mirror row_mask:0xf bank_mask:0xf bound_ctrl:1
	ds_read_b128 v[214:217], v183 offset:15360
	v_pk_fma_f32 v[146:147], v[154:155], v[130:131], v[146:147] op_sel_hi:[0,1,1]
	v_pk_fma_f32 v[148:149], v[154:155], v[222:223], v[148:149] op_sel_hi:[0,1,1]
	ds_read_b128 v[218:221], v183 offset:15392
	ds_read_b128 v[232:235], v155 offset:15360
	ds_read2_b32 v[242:243], v186 offset0:160 offset1:176
	s_waitcnt lgkmcnt(6)
	v_pk_mul_f32 v[150:151], v[146:147], v[190:191]
	v_pk_fma_f32 v[150:151], v[148:149], v[198:199], v[150:151]
	v_pk_mul_f32 v[152:153], v[146:147], v[236:237]
	v_add_f32_e32 v154, v150, v151
	v_pk_fma_f32 v[152:153], v[148:149], v[238:239], v[152:153]
	v_pk_mul_f32 v[142:143], v[146:147], v[192:193]
	v_add_f32_dpp v154, v154, v154 quad_perm:[1,0,3,2] row_mask:0xf bank_mask:0xf bound_ctrl:1
	v_pk_mul_f32 v[144:145], v[148:149], v[200:201]
	v_add_f32_e32 v164, v152, v153
	v_add_f32_dpp v154, v154, v154 quad_perm:[2,3,0,1] row_mask:0xf bank_mask:0xf bound_ctrl:1
	v_pk_fma_f32 v[142:143], v[240:241], v[196:197], v[142:143] op_sel:[1,0,0] op_sel_hi:[1,1,1]
	v_pk_fma_f32 v[144:145], v[240:241], v[204:205], v[144:145] op_sel:[1,0,0] op_sel_hi:[1,1,1]
	v_add_f32_dpp v154, v154, v154 row_half_mirror row_mask:0xf bank_mask:0xf bound_ctrl:1
	ds_read_b128 v[126:129], v182 offset:16896
	ds_read_b128 v[130:133], v182 offset:16928
	v_add_f32_dpp v154, v154, v154 row_mirror row_mask:0xf bank_mask:0xf bound_ctrl:1
	v_pk_fma_f32 v[142:143], v[154:155], v[194:195], v[142:143] op_sel_hi:[0,1,1]
	v_pk_fma_f32 v[144:145], v[154:155], v[202:203], v[144:145] op_sel_hi:[0,1,1]
	ds_read_b128 v[134:137], v183 offset:16896
	ds_read_b128 v[222:225], v183 offset:16928
	ds_read_b128 v[236:239], v155 offset:16896
	s_waitcnt lgkmcnt(5)
	v_pk_mul_f32 v[150:151], v[142:143], v[206:207]
	v_pk_fma_f32 v[150:151], v[144:145], v[214:215], v[150:151]
	v_pk_mul_f32 v[152:153], v[142:143], v[228:229]
	v_add_f32_e32 v154, v150, v151
	v_pk_fma_f32 v[152:153], v[144:145], v[230:231], v[152:153]
	v_pk_mul_f32 v[146:147], v[142:143], v[208:209]
	v_add_f32_dpp v154, v154, v154 quad_perm:[1,0,3,2] row_mask:0xf bank_mask:0xf bound_ctrl:1
	v_pk_mul_f32 v[148:149], v[144:145], v[216:217]
	v_add_f32_e32 v165, v152, v153
	v_add_f32_dpp v154, v154, v154 quad_perm:[2,3,0,1] row_mask:0xf bank_mask:0xf bound_ctrl:1
	v_pk_fma_f32 v[146:147], v[242:243], v[212:213], v[146:147] op_sel:[0,0,0] op_sel_hi:[0,1,1]
	v_pk_fma_f32 v[148:149], v[242:243], v[220:221], v[148:149] op_sel:[0,0,0] op_sel_hi:[0,1,1]
	v_add_f32_dpp v154, v154, v154 row_half_mirror row_mask:0xf bank_mask:0xf bound_ctrl:1
	ds_read_b128 v[190:193], v182 offset:18432
	ds_read_b128 v[194:197], v182 offset:18464
	v_add_f32_dpp v154, v154, v154 row_mirror row_mask:0xf bank_mask:0xf bound_ctrl:1
	ds_read_b128 v[198:201], v183 offset:18432
	v_pk_fma_f32 v[146:147], v[154:155], v[210:211], v[146:147] op_sel_hi:[0,1,1]
	v_pk_fma_f32 v[148:149], v[154:155], v[218:219], v[148:149] op_sel_hi:[0,1,1]
	ds_read_b128 v[202:205], v183 offset:18464
	ds_read_b128 v[228:231], v155 offset:18432
	ds_read2_b32 v[240:241], v186 offset0:192 offset1:208
	s_waitcnt lgkmcnt(6)
	v_pk_mul_f32 v[150:151], v[146:147], v[126:127]
	v_pk_fma_f32 v[150:151], v[148:149], v[134:135], v[150:151]
	v_pk_mul_f32 v[152:153], v[146:147], v[232:233]
	v_add_f32_e32 v154, v150, v151
	v_pk_fma_f32 v[152:153], v[148:149], v[234:235], v[152:153]
	v_pk_mul_f32 v[142:143], v[146:147], v[128:129]
	v_add_f32_dpp v154, v154, v154 quad_perm:[1,0,3,2] row_mask:0xf bank_mask:0xf bound_ctrl:1
	v_pk_mul_f32 v[144:145], v[148:149], v[136:137]
	v_add_f32_e32 v166, v152, v153
	v_add_f32_dpp v154, v154, v154 quad_perm:[2,3,0,1] row_mask:0xf bank_mask:0xf bound_ctrl:1
	v_pk_fma_f32 v[142:143], v[242:243], v[132:133], v[142:143] op_sel:[1,0,0] op_sel_hi:[1,1,1]
	v_pk_fma_f32 v[144:145], v[242:243], v[224:225], v[144:145] op_sel:[1,0,0] op_sel_hi:[1,1,1]
	v_add_f32_dpp v154, v154, v154 row_half_mirror row_mask:0xf bank_mask:0xf bound_ctrl:1
	ds_read_b128 v[206:209], v182 offset:19968
	ds_read_b128 v[210:213], v182 offset:20000
	v_add_f32_dpp v154, v154, v154 row_mirror row_mask:0xf bank_mask:0xf bound_ctrl:1
	v_pk_fma_f32 v[142:143], v[154:155], v[130:131], v[142:143] op_sel_hi:[0,1,1]
	v_pk_fma_f32 v[144:145], v[154:155], v[222:223], v[144:145] op_sel_hi:[0,1,1]
	ds_read_b128 v[214:217], v183 offset:19968
	ds_read_b128 v[218:221], v183 offset:20000
	ds_read_b128 v[232:235], v155 offset:19968
	s_waitcnt lgkmcnt(5)
; __device__ __forceinline__ void wkv_phase(const WkvT& W, unsigned char* lds) {
;     ...
;                 for (int t = 0; t < 32; ++t) {
;                     const f32x2 a2 = {nA[0], nA[1]}, w2 = {nA[2], nA[3]}, b2 = {nB[0], nB[1]}, k2 = {nB[2], nB[3]}, r2 = nr; const float v = nv;
;                     if (t + 1 < 32) { nA = *(const f32x4*)(pp + (t + 1) * 384); nB = *(const f32x4*)(pp + (t + 1) * 384 + 4); nr = *(const f32x2*)(pp + (t + 1) * 384 + 8); nv = pv[(t + 1) * 16]; }
;                     float S0 = S.x, S1 = S.y;
;                     float d = S0 * a2.x; d = __builtin_fmaf(S1, a2.y, d);
;                     float t0 = S0 * w2.x; t0 = __builtin_fmaf(v, k2.x, t0); asm volatile("" : "+v"(t0));
;                     float t1 = S1 * w2.y; t1 = __builtin_fmaf(v, k2.y, t1); asm volatile("" : "+v"(t1));
;                     float yprev; const float sa = wkv_reduce(d, ep, yprev);
;                     S0 = __builtin_fmaf(sa, b2.x, t0); asm volatile("" : "+v"(S0));
;                     S1 = __builtin_fmaf(sa, b2.y, t1); asm volatile("" : "+v"(S1));
;                     ep = S0 * r2.x; ep = __builtin_fmaf(S1, r2.y, ep);
;                     S.x = S0; S.y = S1;
;                     if (t >= 1) { const bool hit = oddrow && ((lane & 15) == ((t - 1) & 15)); if (t <= 16) yk0 = hit ? yprev : yk0; else yk1 = hit ? yprev : yk1; }
;                 }
	v_pk_mul_f32 v[150:151], v[142:143], v[190:191]
	v_pk_fma_f32 v[150:151], v[144:145], v[198:199], v[150:151]
	v_pk_mul_f32 v[152:153], v[142:143], v[236:237]
	v_add_f32_e32 v154, v150, v151
	v_pk_fma_f32 v[152:153], v[144:145], v[238:239], v[152:153]
	v_pk_mul_f32 v[146:147], v[142:143], v[192:193]
	v_add_f32_dpp v154, v154, v154 quad_perm:[1,0,3,2] row_mask:0xf bank_mask:0xf bound_ctrl:1
	v_pk_mul_f32 v[148:149], v[144:145], v[200:201]
	v_add_f32_e32 v167, v152, v153
	v_add_f32_dpp v154, v154, v154 quad_perm:[2,3,0,1] row_mask:0xf bank_mask:0xf bound_ctrl:1
	v_pk_fma_f32 v[146:147], v[240:241], v[196:197], v[146:147] op_sel:[0,0,0] op_sel_hi:[0,1,1]
	v_pk_fma_f32 v[148:149], v[240:241], v[204:205], v[148:149] op_sel:[0,0,0] op_sel_hi:[0,1,1]
	v_add_f32_dpp v154, v154, v154 row_half_mirror row_mask:0xf bank_mask:0xf bound_ctrl:1
	ds_read_b128 v[126:129], v182 offset:21504
	ds_read_b128 v[130:133], v182 offset:21536
	v_add_f32_dpp v154, v154, v154 row_mirror row_mask:0xf bank_mask:0xf bound_ctrl:1
	ds_read_b128 v[134:137], v183 offset:21504
	v_pk_fma_f32 v[146:147], v[154:155], v[194:195], v[146:147] op_sel_hi:[0,1,1]
	v_pk_fma_f32 v[148:149], v[154:155], v[202:203], v[148:149] op_sel_hi:[0,1,1]
	ds_read_b128 v[222:225], v183 offset:21536
	ds_read_b128 v[236:239], v155 offset:21504
	ds_read2_b32 v[242:243], v186 offset0:224 offset1:240
	s_waitcnt lgkmcnt(6)
	v_pk_mul_f32 v[150:151], v[146:147], v[206:207]
	v_pk_fma_f32 v[150:151], v[148:149], v[214:215], v[150:151]
	v_pk_mul_f32 v[152:153], v[146:147], v[228:229]
	v_add_f32_e32 v154, v150, v151
	v_pk_fma_f32 v[152:153], v[148:149], v[230:231], v[152:153]
	v_pk_mul_f32 v[142:143], v[146:147], v[208:209]
	v_add_f32_dpp v154, v154, v154 quad_perm:[1,0,3,2] row_mask:0xf bank_mask:0xf bound_ctrl:1
	v_pk_mul_f32 v[144:145], v[148:149], v[216:217]
	v_add_f32_e32 v168, v152, v153
	v_add_f32_dpp v154, v154, v154 quad_perm:[2,3,0,1] row_mask:0xf bank_mask:0xf bound_ctrl:1
	v_pk_fma_f32 v[142:143], v[240:241], v[212:213], v[142:143] op_sel:[1,0,0] op_sel_hi:[1,1,1]
	v_pk_fma_f32 v[144:145], v[240:241], v[220:221], v[144:145] op_sel:[1,0,0] op_sel_hi:[1,1,1]
	v_add_f32_dpp v154, v154, v154 row_half_mirror row_mask:0xf bank_mask:0xf bound_ctrl:1
	ds_read_b128 v[190:193], v182 offset:23040
	ds_read_b128 v[194:197], v182 offset:23072
	v_add_f32_dpp v154, v154, v154 row_mirror row_mask:0xf bank_mask:0xf bound_ctrl:1
	v_pk_fma_f32 v[142:143], v[154:155], v[210:211], v[142:143] op_sel_hi:[0,1,1]
	v_pk_fma_f32 v[144:145], v[154:155], v[218:219], v[144:145] op_sel_hi:[0,1,1]
	ds_read_b128 v[198:201], v183 offset:23040
	ds_read_b128 v[202:205], v183 offset:23072
	ds_read_b128 v[228:231], v155 offset:23040
	s_waitcnt lgkmcnt(5)
	v_pk_mul_f32 v[150:151], v[142:143], v[126:127]
	v_pk_fma_f32 v[150:151], v[144:145], v[134:135], v[150:151]
	v_pk_mul_f32 v[152:153], v[142:143], v[232:233]
	v_add_f32_e32 v154, v150, v151
	v_pk_fma_f32 v[152:153], v[144:145], v[234:235], v[152:153]
	v_pk_mul_f32 v[146:147], v[142:143], v[128:129]
	v_add_f32_dpp v154, v154, v154 quad_perm:[1,0,3,2] row_mask:0xf bank_mask:0xf bound_ctrl:1
	v_pk_mul_f32 v[148:149], v[144:145], v[136:137]
	v_add_f32_e32 v169, v152, v153
	v_add_f32_dpp v154, v154, v154 quad_perm:[2,3,0,1] row_mask:0xf bank_mask:0xf bound_ctrl:1
	v_pk_fma_f32 v[146:147], v[242:243], v[132:133], v[146:147] op_sel:[0,0,0] op_sel_hi:[0,1,1]
	v_pk_fma_f32 v[148:149], v[242:243], v[224:225], v[148:149] op_sel:[0,0,0] op_sel_hi:[0,1,1]
	v_add_f32_dpp v154, v154, v154 row_half_mirror row_mask:0xf bank_mask:0xf bound_ctrl:1
	ds_read_b128 v[206:209], v182 offset:24576
	ds_read_b128 v[210:213], v182 offset:24608
	v_add_f32_dpp v154, v154, v154 row_mirror row_mask:0xf bank_mask:0xf bound_ctrl:1
	ds_read_b128 v[214:217], v183 offset:24576
	v_pk_fma_f32 v[146:147], v[154:155], v[130:131], v[146:147] op_sel_hi:[0,1,1]
	v_pk_fma_f32 v[148:149], v[154:155], v[222:223], v[148:149] op_sel_hi:[0,1,1]
	ds_read_b128 v[218:221], v183 offset:24608
	ds_read_b128 v[232:235], v155 offset:24576
	ds_read2_b32 v[240:241], v189 offset0:0 offset1:16
	s_waitcnt lgkmcnt(6)
	v_pk_mul_f32 v[150:151], v[146:147], v[190:191]
	v_pk_fma_f32 v[150:151], v[148:149], v[198:199], v[150:151]
	v_pk_mul_f32 v[152:153], v[146:147], v[236:237]
	v_add_f32_e32 v154, v150, v151
	v_pk_fma_f32 v[152:153], v[148:149], v[238:239], v[152:153]
	v_pk_mul_f32 v[142:143], v[146:147], v[192:193]
	v_add_f32_dpp v154, v154, v154 quad_perm:[1,0,3,2] row_mask:0xf bank_mask:0xf bound_ctrl:1
	v_pk_mul_f32 v[144:145], v[148:149], v[200:201]
	v_add_f32_e32 v170, v152, v153
	v_add_f32_dpp v154, v154, v154 quad_perm:[2,3,0,1] row_mask:0xf bank_mask:0xf bound_ctrl:1
	v_pk_fma_f32 v[142:143], v[242:243], v[196:197], v[142:143] op_sel:[1,0,0] op_sel_hi:[1,1,1]
	v_pk_fma_f32 v[144:145], v[242:243], v[204:205], v[144:145] op_sel:[1,0,0] op_sel_hi:[1,1,1]
	v_add_f32_dpp v154, v154, v154 row_half_mirror row_mask:0xf bank_mask:0xf bound_ctrl:1
	ds_read_b128 v[126:129], v182 offset:26112
	ds_read_b128 v[130:133], v182 offset:26144
	v_add_f32_dpp v154, v154, v154 row_mirror row_mask:0xf bank_mask:0xf bound_ctrl:1
	v_pk_fma_f32 v[142:143], v[154:155], v[194:195], v[142:143] op_sel_hi:[0,1,1]
	v_pk_fma_f32 v[144:145], v[154:155], v[202:203], v[144:145] op_sel_hi:[0,1,1]
	ds_read_b128 v[134:137], v183 offset:26112
	ds_read_b128 v[222:225], v183 offset:26144
	ds_read_b128 v[236:239], v155 offset:26112
	s_waitcnt lgkmcnt(5)
; __device__ __forceinline__ void wkv_phase(const WkvT& W, unsigned char* lds) {
;     ...
;                 for (int t = 0; t < 32; ++t) {
;                     const f32x2 a2 = {nA[0], nA[1]}, w2 = {nA[2], nA[3]}, b2 = {nB[0], nB[1]}, k2 = {nB[2], nB[3]}, r2 = nr; const float v = nv;
;                     if (t + 1 < 32) { nA = *(const f32x4*)(pp + (t + 1) * 384); nB = *(const f32x4*)(pp + (t + 1) * 384 + 4); nr = *(const f32x2*)(pp + (t + 1) * 384 + 8); nv = pv[(t + 1) * 16]; }
;                     float S0 = S.x, S1 = S.y;
;                     float d = S0 * a2.x; d = __builtin_fmaf(S1, a2.y, d);
;                     float t0 = S0 * w2.x; t0 = __builtin_fmaf(v, k2.x, t0); asm volatile("" : "+v"(t0));
;                     float t1 = S1 * w2.y; t1 = __builtin_fmaf(v, k2.y, t1); asm volatile("" : "+v"(t1));
;                     float yprev; const float sa = wkv_reduce(d, ep, yprev);
;                     S0 = __builtin_fmaf(sa, b2.x, t0); asm volatile("" : "+v"(S0));
;                     S1 = __builtin_fmaf(sa, b2.y, t1); asm volatile("" : "+v"(S1));
;                     ep = S0 * r2.x; ep = __builtin_fmaf(S1, r2.y, ep);
;                     S.x = S0; S.y = S1;
;                     if (t >= 1) { const bool hit = oddrow && ((lane & 15) == ((t - 1) & 15)); if (t <= 16) yk0 = hit ? yprev : yk0; else yk1 = hit ? yprev : yk1; }
;                 }
;                 { float ylast; (void)wkv_reduce(0.f, ep, ylast); yk1 = (oddrow && (lane & 15) == 15) ? ylast : yk1; }
;                 if (oddrow) { sY[bi * 512 + (lane & 15) * 16 + il] = yk0; sY[bi * 512 + (16 + (lane & 15)) * 16 + il] = yk1; }
	v_pk_mul_f32 v[150:151], v[142:143], v[206:207]
	v_pk_fma_f32 v[150:151], v[144:145], v[214:215], v[150:151]
	v_pk_mul_f32 v[152:153], v[142:143], v[228:229]
	v_add_f32_e32 v154, v150, v151
	v_pk_fma_f32 v[152:153], v[144:145], v[230:231], v[152:153]
	v_pk_mul_f32 v[146:147], v[142:143], v[208:209]
	v_add_f32_dpp v154, v154, v154 quad_perm:[1,0,3,2] row_mask:0xf bank_mask:0xf bound_ctrl:1
	v_pk_mul_f32 v[148:149], v[144:145], v[216:217]
	v_add_f32_e32 v171, v152, v153
	v_add_f32_dpp v154, v154, v154 quad_perm:[2,3,0,1] row_mask:0xf bank_mask:0xf bound_ctrl:1
	v_pk_fma_f32 v[146:147], v[240:241], v[212:213], v[146:147] op_sel:[0,0,0] op_sel_hi:[0,1,1]
	v_pk_fma_f32 v[148:149], v[240:241], v[220:221], v[148:149] op_sel:[0,0,0] op_sel_hi:[0,1,1]
	v_add_f32_dpp v172, v156, v156 row_ror:8 row_mask:0xf bank_mask:0x3
	v_add_f32_dpp v154, v154, v154 row_half_mirror row_mask:0xf bank_mask:0xf bound_ctrl:1
	ds_read_b128 v[190:193], v182 offset:27648
	ds_read_b128 v[194:197], v182 offset:27680
	v_add_f32_dpp v173, v157, v157 row_ror:8 row_mask:0xf bank_mask:0x3
	v_add_f32_dpp v154, v154, v154 row_mirror row_mask:0xf bank_mask:0xf bound_ctrl:1
	ds_read_b128 v[198:201], v183 offset:27648
	v_pk_fma_f32 v[146:147], v[154:155], v[210:211], v[146:147] op_sel_hi:[0,1,1]
	v_pk_fma_f32 v[148:149], v[154:155], v[218:219], v[148:149] op_sel_hi:[0,1,1]
	v_add_f32_dpp v174, v158, v158 row_ror:8 row_mask:0xf bank_mask:0x3
	ds_read_b128 v[202:205], v183 offset:27680
	ds_read_b128 v[228:231], v155 offset:27648
	ds_read2_b32 v[242:243], v189 offset0:32 offset1:48
	v_add_f32_dpp v175, v159, v159 row_ror:8 row_mask:0xf bank_mask:0x3
	s_waitcnt lgkmcnt(6)
	v_pk_mul_f32 v[150:151], v[146:147], v[126:127]
	v_pk_fma_f32 v[150:151], v[148:149], v[134:135], v[150:151]
	v_pk_mul_f32 v[152:153], v[146:147], v[232:233]
	v_add_f32_e32 v154, v150, v151
	v_pk_fma_f32 v[152:153], v[148:149], v[234:235], v[152:153]
	v_pk_mul_f32 v[142:143], v[146:147], v[128:129]
	v_add_f32_dpp v154, v154, v154 quad_perm:[1,0,3,2] row_mask:0xf bank_mask:0xf bound_ctrl:1
	v_pk_mul_f32 v[144:145], v[148:149], v[136:137]
	v_add_f32_e32 v156, v152, v153
	v_add_f32_dpp v154, v154, v154 quad_perm:[2,3,0,1] row_mask:0xf bank_mask:0xf bound_ctrl:1
	v_pk_fma_f32 v[142:143], v[240:241], v[132:133], v[142:143] op_sel:[1,0,0] op_sel_hi:[1,1,1]
	v_pk_fma_f32 v[144:145], v[240:241], v[224:225], v[144:145] op_sel:[1,0,0] op_sel_hi:[1,1,1]
	v_add_f32_dpp v176, v160, v160 row_ror:8 row_mask:0xf bank_mask:0x3
	v_add_f32_dpp v154, v154, v154 row_half_mirror row_mask:0xf bank_mask:0xf bound_ctrl:1
	ds_read_b128 v[206:209], v182 offset:29184
	ds_read_b128 v[210:213], v182 offset:29216
	v_add_f32_dpp v177, v161, v161 row_ror:8 row_mask:0xf bank_mask:0x3
	v_add_f32_dpp v154, v154, v154 row_mirror row_mask:0xf bank_mask:0xf bound_ctrl:1
	v_pk_fma_f32 v[142:143], v[154:155], v[130:131], v[142:143] op_sel_hi:[0,1,1]
	v_pk_fma_f32 v[144:145], v[154:155], v[222:223], v[144:145] op_sel_hi:[0,1,1]
	v_add_f32_dpp v178, v162, v162 row_ror:8 row_mask:0xf bank_mask:0x3
	ds_read_b128 v[214:217], v183 offset:29184
	ds_read_b128 v[218:221], v183 offset:29216
	ds_read_b128 v[232:235], v155 offset:29184
	v_add_f32_dpp v179, v163, v163 row_ror:8 row_mask:0xf bank_mask:0x3
	s_waitcnt lgkmcnt(5)
	v_pk_mul_f32 v[150:151], v[142:143], v[190:191]
	v_pk_fma_f32 v[150:151], v[144:145], v[198:199], v[150:151]
	v_pk_mul_f32 v[152:153], v[142:143], v[236:237]
	v_add_f32_e32 v154, v150, v151
	v_pk_fma_f32 v[152:153], v[144:145], v[238:239], v[152:153]
	v_pk_mul_f32 v[146:147], v[142:143], v[192:193]
	v_add_f32_dpp v154, v154, v154 quad_perm:[1,0,3,2] row_mask:0xf bank_mask:0xf bound_ctrl:1
	v_pk_mul_f32 v[148:149], v[144:145], v[200:201]
	v_add_f32_e32 v157, v152, v153
	v_add_f32_dpp v154, v154, v154 quad_perm:[2,3,0,1] row_mask:0xf bank_mask:0xf bound_ctrl:1
	v_pk_fma_f32 v[146:147], v[242:243], v[196:197], v[146:147] op_sel:[0,0,0] op_sel_hi:[0,1,1]
	v_pk_fma_f32 v[148:149], v[242:243], v[204:205], v[148:149] op_sel:[0,0,0] op_sel_hi:[0,1,1]
	v_add_f32_dpp v172, v164, v164 row_ror:8 row_mask:0xf bank_mask:0xc
	v_add_f32_dpp v154, v154, v154 row_half_mirror row_mask:0xf bank_mask:0xf bound_ctrl:1
	ds_read_b128 v[126:129], v182 offset:30720
	ds_read_b128 v[130:133], v182 offset:30752
	v_add_f32_dpp v173, v165, v165 row_ror:8 row_mask:0xf bank_mask:0xc
	v_add_f32_dpp v154, v154, v154 row_mirror row_mask:0xf bank_mask:0xf bound_ctrl:1
	ds_read_b128 v[134:137], v183 offset:30720
	v_pk_fma_f32 v[146:147], v[154:155], v[194:195], v[146:147] op_sel_hi:[0,1,1]
	v_pk_fma_f32 v[148:149], v[154:155], v[202:203], v[148:149] op_sel_hi:[0,1,1]
	v_add_f32_dpp v174, v166, v166 row_ror:8 row_mask:0xf bank_mask:0xc
	ds_read_b128 v[222:225], v183 offset:30752
	ds_read_b128 v[236:239], v155 offset:30720
	ds_read2_b32 v[240:241], v189 offset0:64 offset1:80
	v_add_f32_dpp v175, v167, v167 row_ror:8 row_mask:0xf bank_mask:0xc
	s_waitcnt lgkmcnt(6)
; __device__ __forceinline__ void wkv_phase(const WkvT& W, unsigned char* lds) {
;     ...
;                 for (int t = 0; t < 32; ++t) {
;                     const f32x2 a2 = {nA[0], nA[1]}, w2 = {nA[2], nA[3]}, b2 = {nB[0], nB[1]}, k2 = {nB[2], nB[3]}, r2 = nr; const float v = nv;
;                     if (t + 1 < 32) { nA = *(const f32x4*)(pp + (t + 1) * 384); nB = *(const f32x4*)(pp + (t + 1) * 384 + 4); nr = *(const f32x2*)(pp + (t + 1) * 384 + 8); nv = pv[(t + 1) * 16]; }
;                     float S0 = S.x, S1 = S.y;
;                     float d = S0 * a2.x; d = __builtin_fmaf(S1, a2.y, d);
;                     float t0 = S0 * w2.x; t0 = __builtin_fmaf(v, k2.x, t0); asm volatile("" : "+v"(t0));
;                     float t1 = S1 * w2.y; t1 = __builtin_fmaf(v, k2.y, t1); asm volatile("" : "+v"(t1));
;                     float yprev; const float sa = wkv_reduce(d, ep, yprev);
;                     S0 = __builtin_fmaf(sa, b2.x, t0); asm volatile("" : "+v"(S0));
;                     S1 = __builtin_fmaf(sa, b2.y, t1); asm volatile("" : "+v"(S1));
;                     ep = S0 * r2.x; ep = __builtin_fmaf(S1, r2.y, ep);
;                     S.x = S0; S.y = S1;
;                     if (t >= 1) { const bool hit = oddrow && ((lane & 15) == ((t - 1) & 15)); if (t <= 16) yk0 = hit ? yprev : yk0; else yk1 = hit ? yprev : yk1; }
;                 }
;                 { float ylast; (void)wkv_reduce(0.f, ep, ylast); yk1 = (oddrow && (lane & 15) == 15) ? ylast : yk1; }
;                 if (oddrow) { sY[bi * 512 + (lane & 15) * 16 + il] = yk0; sY[bi * 512 + (16 + (lane & 15)) * 16 + il] = yk1; }
	v_pk_mul_f32 v[150:151], v[146:147], v[206:207]
	v_pk_fma_f32 v[150:151], v[148:149], v[214:215], v[150:151]
	v_pk_mul_f32 v[152:153], v[146:147], v[228:229]
	v_add_f32_e32 v154, v150, v151
	v_pk_fma_f32 v[152:153], v[148:149], v[230:231], v[152:153]
	v_pk_mul_f32 v[142:143], v[146:147], v[208:209]
	v_add_f32_dpp v154, v154, v154 quad_perm:[1,0,3,2] row_mask:0xf bank_mask:0xf bound_ctrl:1
	v_pk_mul_f32 v[144:145], v[148:149], v[216:217]
	v_add_f32_e32 v158, v152, v153
	v_add_f32_dpp v154, v154, v154 quad_perm:[2,3,0,1] row_mask:0xf bank_mask:0xf bound_ctrl:1
	v_pk_fma_f32 v[142:143], v[242:243], v[212:213], v[142:143] op_sel:[1,0,0] op_sel_hi:[1,1,1]
	v_pk_fma_f32 v[144:145], v[242:243], v[220:221], v[144:145] op_sel:[1,0,0] op_sel_hi:[1,1,1]
	v_add_f32_dpp v176, v168, v168 row_ror:8 row_mask:0xf bank_mask:0xc
	v_add_f32_dpp v154, v154, v154 row_half_mirror row_mask:0xf bank_mask:0xf bound_ctrl:1
	ds_read_b128 v[190:193], v182 offset:32256
	ds_read_b128 v[194:197], v182 offset:32288
	v_add_f32_dpp v177, v169, v169 row_ror:8 row_mask:0xf bank_mask:0xc
	v_add_f32_dpp v154, v154, v154 row_mirror row_mask:0xf bank_mask:0xf bound_ctrl:1
	v_pk_fma_f32 v[142:143], v[154:155], v[210:211], v[142:143] op_sel_hi:[0,1,1]
	v_pk_fma_f32 v[144:145], v[154:155], v[218:219], v[144:145] op_sel_hi:[0,1,1]
	v_add_f32_dpp v178, v170, v170 row_ror:8 row_mask:0xf bank_mask:0xc
	ds_read_b128 v[198:201], v183 offset:32256
	ds_read_b128 v[202:205], v183 offset:32288
	ds_read_b128 v[228:231], v155 offset:32256
	v_add_f32_dpp v179, v171, v171 row_ror:8 row_mask:0xf bank_mask:0xc
	s_waitcnt lgkmcnt(5)
	v_pk_mul_f32 v[150:151], v[142:143], v[126:127]
	v_pk_fma_f32 v[150:151], v[144:145], v[134:135], v[150:151]
	v_pk_mul_f32 v[152:153], v[142:143], v[232:233]
	v_add_f32_e32 v154, v150, v151
	v_pk_fma_f32 v[152:153], v[144:145], v[234:235], v[152:153]
	v_pk_mul_f32 v[146:147], v[142:143], v[128:129]
	v_add_f32_dpp v154, v154, v154 quad_perm:[1,0,3,2] row_mask:0xf bank_mask:0xf bound_ctrl:1
	v_pk_mul_f32 v[148:149], v[144:145], v[136:137]
	v_add_f32_e32 v159, v152, v153
	v_add_f32_dpp v154, v154, v154 quad_perm:[2,3,0,1] row_mask:0xf bank_mask:0xf bound_ctrl:1
	v_pk_fma_f32 v[146:147], v[240:241], v[132:133], v[146:147] op_sel:[0,0,0] op_sel_hi:[0,1,1]
	v_pk_fma_f32 v[148:149], v[240:241], v[224:225], v[148:149] op_sel:[0,0,0] op_sel_hi:[0,1,1]
	v_add_f32_dpp v56, v172, v172 row_half_mirror row_mask:0xf bank_mask:0x5
	v_add_f32_dpp v154, v154, v154 row_half_mirror row_mask:0xf bank_mask:0xf bound_ctrl:1
	ds_read_b128 v[206:209], v182 offset:33792
	ds_read_b128 v[210:213], v182 offset:33824
	v_add_f32_dpp v57, v173, v173 row_half_mirror row_mask:0xf bank_mask:0x5
	v_add_f32_dpp v154, v154, v154 row_mirror row_mask:0xf bank_mask:0xf bound_ctrl:1
	ds_read_b128 v[214:217], v183 offset:33792
	v_pk_fma_f32 v[146:147], v[154:155], v[130:131], v[146:147] op_sel_hi:[0,1,1]
	v_pk_fma_f32 v[148:149], v[154:155], v[222:223], v[148:149] op_sel_hi:[0,1,1]
	v_add_f32_dpp v58, v174, v174 row_half_mirror row_mask:0xf bank_mask:0x5
	ds_read_b128 v[218:221], v183 offset:33824
	ds_read_b128 v[232:235], v155 offset:33792
	ds_read2_b32 v[242:243], v189 offset0:96 offset1:112
	v_add_f32_dpp v59, v175, v175 row_half_mirror row_mask:0xf bank_mask:0x5
	s_waitcnt lgkmcnt(6)
	v_pk_mul_f32 v[150:151], v[146:147], v[190:191]
	v_pk_fma_f32 v[150:151], v[148:149], v[198:199], v[150:151]
	v_pk_mul_f32 v[152:153], v[146:147], v[236:237]
	v_add_f32_e32 v154, v150, v151
	v_pk_fma_f32 v[152:153], v[148:149], v[238:239], v[152:153]
	v_pk_mul_f32 v[142:143], v[146:147], v[192:193]
	v_add_f32_dpp v154, v154, v154 quad_perm:[1,0,3,2] row_mask:0xf bank_mask:0xf bound_ctrl:1
	v_pk_mul_f32 v[144:145], v[148:149], v[200:201]
	v_add_f32_e32 v160, v152, v153
	v_add_f32_dpp v154, v154, v154 quad_perm:[2,3,0,1] row_mask:0xf bank_mask:0xf bound_ctrl:1
	v_pk_fma_f32 v[142:143], v[240:241], v[196:197], v[142:143] op_sel:[1,0,0] op_sel_hi:[1,1,1]
	v_pk_fma_f32 v[144:145], v[240:241], v[204:205], v[144:145] op_sel:[1,0,0] op_sel_hi:[1,1,1]
	v_add_f32_dpp v56, v176, v176 row_half_mirror row_mask:0xf bank_mask:0xa
	v_add_f32_dpp v154, v154, v154 row_half_mirror row_mask:0xf bank_mask:0xf bound_ctrl:1
	ds_read_b128 v[126:129], v182 offset:35328
	ds_read_b128 v[130:133], v182 offset:35360
	v_add_f32_dpp v57, v177, v177 row_half_mirror row_mask:0xf bank_mask:0xa
	v_add_f32_dpp v154, v154, v154 row_mirror row_mask:0xf bank_mask:0xf bound_ctrl:1
	v_pk_fma_f32 v[142:143], v[154:155], v[194:195], v[142:143] op_sel_hi:[0,1,1]
	v_pk_fma_f32 v[144:145], v[154:155], v[202:203], v[144:145] op_sel_hi:[0,1,1]
	v_add_f32_dpp v58, v178, v178 row_half_mirror row_mask:0xf bank_mask:0xa
	ds_read_b128 v[134:137], v183 offset:35328
	ds_read_b128 v[222:225], v183 offset:35360
	ds_read_b128 v[236:239], v155 offset:35328
	v_add_f32_dpp v59, v179, v179 row_half_mirror row_mask:0xf bank_mask:0xa
	s_waitcnt lgkmcnt(5)
; __device__ __forceinline__ void wkv_phase(const WkvT& W, unsigned char* lds) {
;     ...
;                 for (int t = 0; t < 32; ++t) {
;                     const f32x2 a2 = {nA[0], nA[1]}, w2 = {nA[2], nA[3]}, b2 = {nB[0], nB[1]}, k2 = {nB[2], nB[3]}, r2 = nr; const float v = nv;
;                     if (t + 1 < 32) { nA = *(const f32x4*)(pp + (t + 1) * 384); nB = *(const f32x4*)(pp + (t + 1) * 384 + 4); nr = *(const f32x2*)(pp + (t + 1) * 384 + 8); nv = pv[(t + 1) * 16]; }
;                     float S0 = S.x, S1 = S.y;
;                     float d = S0 * a2.x; d = __builtin_fmaf(S1, a2.y, d);
;                     float t0 = S0 * w2.x; t0 = __builtin_fmaf(v, k2.x, t0); asm volatile("" : "+v"(t0));
;                     float t1 = S1 * w2.y; t1 = __builtin_fmaf(v, k2.y, t1); asm volatile("" : "+v"(t1));
;                     float yprev; const float sa = wkv_reduce(d, ep, yprev);
;                     S0 = __builtin_fmaf(sa, b2.x, t0); asm volatile("" : "+v"(S0));
;                     S1 = __builtin_fmaf(sa, b2.y, t1); asm volatile("" : "+v"(S1));
;                     ep = S0 * r2.x; ep = __builtin_fmaf(S1, r2.y, ep);
;                     S.x = S0; S.y = S1;
;                     if (t >= 1) { const bool hit = oddrow && ((lane & 15) == ((t - 1) & 15)); if (t <= 16) yk0 = hit ? yprev : yk0; else yk1 = hit ? yprev : yk1; }
;                 }
;                 { float ylast; (void)wkv_reduce(0.f, ep, ylast); yk1 = (oddrow && (lane & 15) == 15) ? ylast : yk1; }
;                 if (oddrow) { sY[bi * 512 + (lane & 15) * 16 + il] = yk0; sY[bi * 512 + (16 + (lane & 15)) * 16 + il] = yk1; }
	v_pk_mul_f32 v[150:151], v[142:143], v[206:207]
	v_pk_fma_f32 v[150:151], v[144:145], v[214:215], v[150:151]
	v_pk_mul_f32 v[152:153], v[142:143], v[228:229]
	v_add_f32_e32 v154, v150, v151
	v_pk_fma_f32 v[152:153], v[144:145], v[230:231], v[152:153]
	v_pk_mul_f32 v[146:147], v[142:143], v[208:209]
	v_add_f32_dpp v154, v154, v154 quad_perm:[1,0,3,2] row_mask:0xf bank_mask:0xf bound_ctrl:1
	v_pk_mul_f32 v[148:149], v[144:145], v[216:217]
	v_add_f32_e32 v161, v152, v153
	v_add_f32_dpp v154, v154, v154 quad_perm:[2,3,0,1] row_mask:0xf bank_mask:0xf bound_ctrl:1
	v_pk_fma_f32 v[146:147], v[242:243], v[212:213], v[146:147] op_sel:[0,0,0] op_sel_hi:[0,1,1]
	v_pk_fma_f32 v[148:149], v[242:243], v[220:221], v[148:149] op_sel:[0,0,0] op_sel_hi:[0,1,1]
	v_cndmask_b32_e64 v178, v56, v58, s[14:15]
	v_add_f32_dpp v154, v154, v154 row_half_mirror row_mask:0xf bank_mask:0xf bound_ctrl:1
	ds_read_b128 v[190:193], v182 offset:36864
	ds_read_b128 v[194:197], v182 offset:36896
	v_cndmask_b32_e64 v176, v58, v56, s[14:15]
	v_add_f32_dpp v154, v154, v154 row_mirror row_mask:0xf bank_mask:0xf bound_ctrl:1
	ds_read_b128 v[198:201], v183 offset:36864
	v_pk_fma_f32 v[146:147], v[154:155], v[210:211], v[146:147] op_sel_hi:[0,1,1]
	v_pk_fma_f32 v[148:149], v[154:155], v[218:219], v[148:149] op_sel_hi:[0,1,1]
	v_cndmask_b32_e64 v179, v57, v59, s[14:15]
	ds_read_b128 v[202:205], v183 offset:36896
	ds_read_b128 v[228:231], v155 offset:36864
	ds_read2_b32 v[240:241], v189 offset0:128 offset1:144
	v_cndmask_b32_e64 v177, v59, v57, s[14:15]
	s_waitcnt lgkmcnt(6)
	v_pk_mul_f32 v[150:151], v[146:147], v[126:127]
	v_pk_fma_f32 v[150:151], v[148:149], v[134:135], v[150:151]
	v_pk_mul_f32 v[152:153], v[146:147], v[232:233]
	v_add_f32_e32 v154, v150, v151
	v_pk_fma_f32 v[152:153], v[148:149], v[234:235], v[152:153]
	v_pk_mul_f32 v[142:143], v[146:147], v[128:129]
	v_add_f32_dpp v154, v154, v154 quad_perm:[1,0,3,2] row_mask:0xf bank_mask:0xf bound_ctrl:1
	v_pk_mul_f32 v[144:145], v[148:149], v[136:137]
	v_add_f32_e32 v162, v152, v153
	v_add_f32_dpp v154, v154, v154 quad_perm:[2,3,0,1] row_mask:0xf bank_mask:0xf bound_ctrl:1
	v_pk_fma_f32 v[142:143], v[242:243], v[132:133], v[142:143] op_sel:[1,0,0] op_sel_hi:[1,1,1]
	v_pk_fma_f32 v[144:145], v[242:243], v[224:225], v[144:145] op_sel:[1,0,0] op_sel_hi:[1,1,1]
	v_add_f32_dpp v172, v176, v178 quad_perm:[2,3,0,1] row_mask:0xf bank_mask:0xf
	v_add_f32_dpp v154, v154, v154 row_half_mirror row_mask:0xf bank_mask:0xf bound_ctrl:1
	ds_read_b128 v[206:209], v182 offset:38400
	ds_read_b128 v[210:213], v182 offset:38432
	v_add_f32_dpp v173, v177, v179 quad_perm:[2,3,0,1] row_mask:0xf bank_mask:0xf
	v_add_f32_dpp v154, v154, v154 row_mirror row_mask:0xf bank_mask:0xf bound_ctrl:1
	v_pk_fma_f32 v[142:143], v[154:155], v[130:131], v[142:143] op_sel_hi:[0,1,1]
	v_pk_fma_f32 v[144:145], v[154:155], v[222:223], v[144:145] op_sel_hi:[0,1,1]
	v_cndmask_b32_e64 v176, v173, v172, s[16:17]
	ds_read_b128 v[214:217], v183 offset:38400
	ds_read_b128 v[218:221], v183 offset:38432
	ds_read_b128 v[232:235], v155 offset:38400
	v_cndmask_b32_e64 v178, v172, v173, s[16:17]
	s_waitcnt lgkmcnt(5)
	v_pk_mul_f32 v[150:151], v[142:143], v[190:191]
	v_pk_fma_f32 v[150:151], v[144:145], v[198:199], v[150:151]
	v_pk_mul_f32 v[152:153], v[142:143], v[236:237]
	v_add_f32_e32 v154, v150, v151
	v_pk_fma_f32 v[152:153], v[144:145], v[238:239], v[152:153]
	v_pk_mul_f32 v[146:147], v[142:143], v[192:193]
	v_add_f32_dpp v154, v154, v154 quad_perm:[1,0,3,2] row_mask:0xf bank_mask:0xf bound_ctrl:1
	v_pk_mul_f32 v[148:149], v[144:145], v[200:201]
	v_add_f32_e32 v163, v152, v153
	v_add_f32_dpp v154, v154, v154 quad_perm:[2,3,0,1] row_mask:0xf bank_mask:0xf bound_ctrl:1
	v_pk_fma_f32 v[146:147], v[240:241], v[196:197], v[146:147] op_sel:[0,0,0] op_sel_hi:[0,1,1]
	v_pk_fma_f32 v[148:149], v[240:241], v[204:205], v[148:149] op_sel:[0,0,0] op_sel_hi:[0,1,1]
	v_add_f32_dpp v180, v176, v178 quad_perm:[1,0,3,2] row_mask:0xf bank_mask:0xf
	v_add_f32_dpp v154, v154, v154 row_half_mirror row_mask:0xf bank_mask:0xf bound_ctrl:1
	ds_read_b128 v[126:129], v182 offset:39936
	ds_read_b128 v[130:133], v182 offset:39968
	v_add_f32_dpp v154, v154, v154 row_mirror row_mask:0xf bank_mask:0xf bound_ctrl:1
	ds_read_b128 v[134:137], v183 offset:39936
	v_pk_fma_f32 v[146:147], v[154:155], v[194:195], v[146:147] op_sel_hi:[0,1,1]
	v_pk_fma_f32 v[148:149], v[154:155], v[202:203], v[148:149] op_sel_hi:[0,1,1]
	ds_read_b128 v[222:225], v183 offset:39968
	ds_read_b128 v[236:239], v155 offset:39936
	ds_read2_b32 v[242:243], v189 offset0:160 offset1:176
	s_waitcnt lgkmcnt(6)
	v_pk_mul_f32 v[150:151], v[146:147], v[206:207]
	v_pk_fma_f32 v[150:151], v[148:149], v[214:215], v[150:151]
	v_pk_mul_f32 v[152:153], v[146:147], v[228:229]
	v_add_f32_e32 v154, v150, v151
	v_pk_fma_f32 v[152:153], v[148:149], v[230:231], v[152:153]
	v_pk_mul_f32 v[142:143], v[146:147], v[208:209]
	v_add_f32_dpp v154, v154, v154 quad_perm:[1,0,3,2] row_mask:0xf bank_mask:0xf bound_ctrl:1
	v_pk_mul_f32 v[144:145], v[148:149], v[216:217]
	v_add_f32_e32 v164, v152, v153
	v_add_f32_dpp v154, v154, v154 quad_perm:[2,3,0,1] row_mask:0xf bank_mask:0xf bound_ctrl:1
	v_pk_fma_f32 v[142:143], v[240:241], v[212:213], v[142:143] op_sel:[1,0,0] op_sel_hi:[1,1,1]
	v_pk_fma_f32 v[144:145], v[240:241], v[220:221], v[144:145] op_sel:[1,0,0] op_sel_hi:[1,1,1]
	v_add_f32_dpp v172, v156, v156 row_ror:8 row_mask:0xf bank_mask:0x3
	v_add_f32_dpp v154, v154, v154 row_half_mirror row_mask:0xf bank_mask:0xf bound_ctrl:1
	ds_read_b128 v[190:193], v182 offset:41472
	ds_read_b128 v[194:197], v182 offset:41504
	v_add_f32_dpp v173, v157, v157 row_ror:8 row_mask:0xf bank_mask:0x3
	v_add_f32_dpp v154, v154, v154 row_mirror row_mask:0xf bank_mask:0xf bound_ctrl:1
	v_pk_fma_f32 v[142:143], v[154:155], v[210:211], v[142:143] op_sel_hi:[0,1,1]
	v_pk_fma_f32 v[144:145], v[154:155], v[218:219], v[144:145] op_sel_hi:[0,1,1]
	v_add_f32_dpp v174, v158, v158 row_ror:8 row_mask:0xf bank_mask:0x3
	ds_read_b128 v[198:201], v183 offset:41472
	ds_read_b128 v[202:205], v183 offset:41504
	ds_read_b128 v[228:231], v155 offset:41472
	v_add_f32_dpp v175, v159, v159 row_ror:8 row_mask:0xf bank_mask:0x3
	s_waitcnt lgkmcnt(5)
; __device__ __forceinline__ void wkv_phase(const WkvT& W, unsigned char* lds) {
;     ...
;                 for (int t = 0; t < 32; ++t) {
;                     const f32x2 a2 = {nA[0], nA[1]}, w2 = {nA[2], nA[3]}, b2 = {nB[0], nB[1]}, k2 = {nB[2], nB[3]}, r2 = nr; const float v = nv;
;                     if (t + 1 < 32) { nA = *(const f32x4*)(pp + (t + 1) * 384); nB = *(const f32x4*)(pp + (t + 1) * 384 + 4); nr = *(const f32x2*)(pp + (t + 1) * 384 + 8); nv = pv[(t + 1) * 16]; }
;                     float S0 = S.x, S1 = S.y;
;                     float d = S0 * a2.x; d = __builtin_fmaf(S1, a2.y, d);
;                     float t0 = S0 * w2.x; t0 = __builtin_fmaf(v, k2.x, t0); asm volatile("" : "+v"(t0));
;                     float t1 = S1 * w2.y; t1 = __builtin_fmaf(v, k2.y, t1); asm volatile("" : "+v"(t1));
;                     float yprev; const float sa = wkv_reduce(d, ep, yprev);
;                     S0 = __builtin_fmaf(sa, b2.x, t0); asm volatile("" : "+v"(S0));
;                     S1 = __builtin_fmaf(sa, b2.y, t1); asm volatile("" : "+v"(S1));
;                     ep = S0 * r2.x; ep = __builtin_fmaf(S1, r2.y, ep);
;                     S.x = S0; S.y = S1;
;                     if (t >= 1) { const bool hit = oddrow && ((lane & 15) == ((t - 1) & 15)); if (t <= 16) yk0 = hit ? yprev : yk0; else yk1 = hit ? yprev : yk1; }
;                 }
;                 { float ylast; (void)wkv_reduce(0.f, ep, ylast); yk1 = (oddrow && (lane & 15) == 15) ? ylast : yk1; }
;                 if (oddrow) { sY[bi * 512 + (lane & 15) * 16 + il] = yk0; sY[bi * 512 + (16 + (lane & 15)) * 16 + il] = yk1; }
	v_pk_mul_f32 v[150:151], v[142:143], v[126:127]
	v_pk_fma_f32 v[150:151], v[144:145], v[134:135], v[150:151]
	v_pk_mul_f32 v[152:153], v[142:143], v[232:233]
	v_add_f32_e32 v154, v150, v151
	v_pk_fma_f32 v[152:153], v[144:145], v[234:235], v[152:153]
	v_pk_mul_f32 v[146:147], v[142:143], v[128:129]
	v_add_f32_dpp v154, v154, v154 quad_perm:[1,0,3,2] row_mask:0xf bank_mask:0xf bound_ctrl:1
	v_pk_mul_f32 v[148:149], v[144:145], v[136:137]
	v_add_f32_e32 v165, v152, v153
	v_add_f32_dpp v154, v154, v154 quad_perm:[2,3,0,1] row_mask:0xf bank_mask:0xf bound_ctrl:1
	v_pk_fma_f32 v[146:147], v[242:243], v[132:133], v[146:147] op_sel:[0,0,0] op_sel_hi:[0,1,1]
	v_pk_fma_f32 v[148:149], v[242:243], v[224:225], v[148:149] op_sel:[0,0,0] op_sel_hi:[0,1,1]
	v_add_f32_dpp v176, v160, v160 row_ror:8 row_mask:0xf bank_mask:0x3
	v_add_f32_dpp v154, v154, v154 row_half_mirror row_mask:0xf bank_mask:0xf bound_ctrl:1
	ds_read_b128 v[206:209], v182 offset:43008
	ds_read_b128 v[210:213], v182 offset:43040
	v_add_f32_dpp v177, v161, v161 row_ror:8 row_mask:0xf bank_mask:0x3
	v_add_f32_dpp v154, v154, v154 row_mirror row_mask:0xf bank_mask:0xf bound_ctrl:1
	ds_read_b128 v[214:217], v183 offset:43008
	v_pk_fma_f32 v[146:147], v[154:155], v[130:131], v[146:147] op_sel_hi:[0,1,1]
	v_pk_fma_f32 v[148:149], v[154:155], v[222:223], v[148:149] op_sel_hi:[0,1,1]
	v_add_f32_dpp v178, v162, v162 row_ror:8 row_mask:0xf bank_mask:0x3
	ds_read_b128 v[218:221], v183 offset:43040
	ds_read_b128 v[232:235], v155 offset:43008
	ds_read2_b32 v[240:241], v189 offset0:192 offset1:208
	v_add_f32_dpp v179, v163, v163 row_ror:8 row_mask:0xf bank_mask:0x3
	s_waitcnt lgkmcnt(6)
	v_pk_mul_f32 v[150:151], v[146:147], v[190:191]
	v_pk_fma_f32 v[150:151], v[148:149], v[198:199], v[150:151]
	v_pk_mul_f32 v[152:153], v[146:147], v[236:237]
	v_add_f32_e32 v154, v150, v151
	v_pk_fma_f32 v[152:153], v[148:149], v[238:239], v[152:153]
	v_pk_mul_f32 v[142:143], v[146:147], v[192:193]
	v_add_f32_dpp v154, v154, v154 quad_perm:[1,0,3,2] row_mask:0xf bank_mask:0xf bound_ctrl:1
	v_pk_mul_f32 v[144:145], v[148:149], v[200:201]
	v_add_f32_e32 v166, v152, v153
	v_add_f32_dpp v154, v154, v154 quad_perm:[2,3,0,1] row_mask:0xf bank_mask:0xf bound_ctrl:1
	v_pk_fma_f32 v[142:143], v[242:243], v[196:197], v[142:143] op_sel:[1,0,0] op_sel_hi:[1,1,1]
	v_pk_fma_f32 v[144:145], v[242:243], v[204:205], v[144:145] op_sel:[1,0,0] op_sel_hi:[1,1,1]
	v_add_f32_dpp v172, v164, v164 row_ror:8 row_mask:0xf bank_mask:0xc
	v_add_f32_dpp v154, v154, v154 row_half_mirror row_mask:0xf bank_mask:0xf bound_ctrl:1
	ds_read_b128 v[126:129], v182 offset:44544
	ds_read_b128 v[130:133], v182 offset:44576
	v_add_f32_dpp v154, v154, v154 row_mirror row_mask:0xf bank_mask:0xf bound_ctrl:1
	v_pk_fma_f32 v[142:143], v[154:155], v[194:195], v[142:143] op_sel_hi:[0,1,1]
	v_pk_fma_f32 v[144:145], v[154:155], v[202:203], v[144:145] op_sel_hi:[0,1,1]
	ds_read_b128 v[134:137], v183 offset:44544
	ds_read_b128 v[222:225], v183 offset:44576
	ds_read_b128 v[236:239], v155 offset:44544
	s_waitcnt lgkmcnt(5)
	v_pk_mul_f32 v[150:151], v[142:143], v[206:207]
	v_pk_fma_f32 v[150:151], v[144:145], v[214:215], v[150:151]
	v_pk_mul_f32 v[152:153], v[142:143], v[228:229]
	v_add_f32_e32 v154, v150, v151
	v_pk_fma_f32 v[152:153], v[144:145], v[230:231], v[152:153]
	v_pk_mul_f32 v[146:147], v[142:143], v[208:209]
	v_add_f32_dpp v154, v154, v154 quad_perm:[1,0,3,2] row_mask:0xf bank_mask:0xf bound_ctrl:1
	v_pk_mul_f32 v[148:149], v[144:145], v[216:217]
	v_add_f32_e32 v167, v152, v153
	v_add_f32_dpp v154, v154, v154 quad_perm:[2,3,0,1] row_mask:0xf bank_mask:0xf bound_ctrl:1
	v_pk_fma_f32 v[146:147], v[240:241], v[212:213], v[146:147] op_sel:[0,0,0] op_sel_hi:[0,1,1]
	v_pk_fma_f32 v[148:149], v[240:241], v[220:221], v[148:149] op_sel:[0,0,0] op_sel_hi:[0,1,1]
	v_add_f32_dpp v173, v165, v165 row_ror:8 row_mask:0xf bank_mask:0xc
	v_add_f32_dpp v154, v154, v154 row_half_mirror row_mask:0xf bank_mask:0xf bound_ctrl:1
	ds_read_b128 v[190:193], v182 offset:46080
	ds_read_b128 v[194:197], v182 offset:46112
	v_add_f32_dpp v154, v154, v154 row_mirror row_mask:0xf bank_mask:0xf bound_ctrl:1
	ds_read_b128 v[198:201], v183 offset:46080
	v_pk_fma_f32 v[146:147], v[154:155], v[210:211], v[146:147] op_sel_hi:[0,1,1]
	v_pk_fma_f32 v[148:149], v[154:155], v[218:219], v[148:149] op_sel_hi:[0,1,1]
	ds_read_b128 v[202:205], v183 offset:46112
	ds_read_b128 v[228:231], v155 offset:46080
	ds_read2_b32 v[242:243], v189 offset0:224 offset1:240
	s_waitcnt lgkmcnt(6)
; __device__ __forceinline__ void wkv_phase(const WkvT& W, unsigned char* lds) {
;     ...
;                 for (int t = 0; t < 32; ++t) {
;                     const f32x2 a2 = {nA[0], nA[1]}, w2 = {nA[2], nA[3]}, b2 = {nB[0], nB[1]}, k2 = {nB[2], nB[3]}, r2 = nr; const float v = nv;
;                     if (t + 1 < 32) { nA = *(const f32x4*)(pp + (t + 1) * 384); nB = *(const f32x4*)(pp + (t + 1) * 384 + 4); nr = *(const f32x2*)(pp + (t + 1) * 384 + 8); nv = pv[(t + 1) * 16]; }
;                     float S0 = S.x, S1 = S.y;
;                     float d = S0 * a2.x; d = __builtin_fmaf(S1, a2.y, d);
;                     float t0 = S0 * w2.x; t0 = __builtin_fmaf(v, k2.x, t0); asm volatile("" : "+v"(t0));
;                     float t1 = S1 * w2.y; t1 = __builtin_fmaf(v, k2.y, t1); asm volatile("" : "+v"(t1));
;                     float yprev; const float sa = wkv_reduce(d, ep, yprev);
;                     S0 = __builtin_fmaf(sa, b2.x, t0); asm volatile("" : "+v"(S0));
;                     S1 = __builtin_fmaf(sa, b2.y, t1); asm volatile("" : "+v"(S1));
;                     ep = S0 * r2.x; ep = __builtin_fmaf(S1, r2.y, ep);
;                     S.x = S0; S.y = S1;
;                     if (t >= 1) { const bool hit = oddrow && ((lane & 15) == ((t - 1) & 15)); if (t <= 16) yk0 = hit ? yprev : yk0; else yk1 = hit ? yprev : yk1; }
;                 }
;                 { float ylast; (void)wkv_reduce(0.f, ep, ylast); yk1 = (oddrow && (lane & 15) == 15) ? ylast : yk1; }
;                 if (oddrow) { sY[bi * 512 + (lane & 15) * 16 + il] = yk0; sY[bi * 512 + (16 + (lane & 15)) * 16 + il] = yk1; }
	v_pk_mul_f32 v[150:151], v[146:147], v[126:127]
	v_pk_fma_f32 v[150:151], v[148:149], v[134:135], v[150:151]
	v_pk_mul_f32 v[152:153], v[146:147], v[232:233]
	v_add_f32_e32 v154, v150, v151
	v_pk_fma_f32 v[152:153], v[148:149], v[234:235], v[152:153]
	v_pk_mul_f32 v[142:143], v[146:147], v[128:129]
	v_add_f32_dpp v154, v154, v154 quad_perm:[1,0,3,2] row_mask:0xf bank_mask:0xf bound_ctrl:1
	v_pk_mul_f32 v[144:145], v[148:149], v[136:137]
	v_add_f32_e32 v168, v152, v153
	v_add_f32_dpp v154, v154, v154 quad_perm:[2,3,0,1] row_mask:0xf bank_mask:0xf bound_ctrl:1
	v_pk_fma_f32 v[142:143], v[240:241], v[132:133], v[142:143] op_sel:[1,0,0] op_sel_hi:[1,1,1]
	v_pk_fma_f32 v[144:145], v[240:241], v[224:225], v[144:145] op_sel:[1,0,0] op_sel_hi:[1,1,1]
	v_add_f32_dpp v174, v166, v166 row_ror:8 row_mask:0xf bank_mask:0xc
	v_add_f32_dpp v154, v154, v154 row_half_mirror row_mask:0xf bank_mask:0xf bound_ctrl:1
	ds_read_b128 v[206:209], v182 offset:47616
	ds_read_b128 v[210:213], v182 offset:47648
	v_add_f32_dpp v154, v154, v154 row_mirror row_mask:0xf bank_mask:0xf bound_ctrl:1
	v_pk_fma_f32 v[142:143], v[154:155], v[130:131], v[142:143] op_sel_hi:[0,1,1]
	v_pk_fma_f32 v[144:145], v[154:155], v[222:223], v[144:145] op_sel_hi:[0,1,1]
	ds_read_b128 v[214:217], v183 offset:47616
	ds_read_b128 v[218:221], v183 offset:47648
	ds_read_b128 v[232:235], v155 offset:47616
	s_waitcnt lgkmcnt(5)
	v_pk_mul_f32 v[150:151], v[142:143], v[190:191]
	v_pk_fma_f32 v[150:151], v[144:145], v[198:199], v[150:151]
	v_pk_mul_f32 v[152:153], v[142:143], v[236:237]
	v_add_f32_e32 v154, v150, v151
	v_pk_fma_f32 v[152:153], v[144:145], v[238:239], v[152:153]
	v_pk_mul_f32 v[146:147], v[142:143], v[192:193]
	v_add_f32_dpp v154, v154, v154 quad_perm:[1,0,3,2] row_mask:0xf bank_mask:0xf bound_ctrl:1
	v_pk_mul_f32 v[148:149], v[144:145], v[200:201]
	v_add_f32_e32 v169, v152, v153
	v_add_f32_dpp v154, v154, v154 quad_perm:[2,3,0,1] row_mask:0xf bank_mask:0xf bound_ctrl:1
	v_pk_fma_f32 v[146:147], v[242:243], v[196:197], v[146:147] op_sel:[0,0,0] op_sel_hi:[0,1,1]
	v_pk_fma_f32 v[148:149], v[242:243], v[204:205], v[148:149] op_sel:[0,0,0] op_sel_hi:[0,1,1]
	v_add_f32_dpp v175, v167, v167 row_ror:8 row_mask:0xf bank_mask:0xc
	v_add_f32_dpp v154, v154, v154 row_half_mirror row_mask:0xf bank_mask:0xf bound_ctrl:1
	s_nop 1
	v_add_f32_dpp v154, v154, v154 row_mirror row_mask:0xf bank_mask:0xf bound_ctrl:1
	v_pk_fma_f32 v[146:147], v[154:155], v[194:195], v[146:147] op_sel_hi:[0,1,1]
	v_pk_fma_f32 v[148:149], v[154:155], v[202:203], v[148:149] op_sel_hi:[0,1,1]
	s_waitcnt lgkmcnt(0)
	v_pk_mul_f32 v[150:151], v[146:147], v[206:207]
	v_pk_fma_f32 v[150:151], v[148:149], v[214:215], v[150:151]
	v_pk_mul_f32 v[152:153], v[146:147], v[228:229]
	v_add_f32_e32 v154, v150, v151
	v_pk_fma_f32 v[152:153], v[148:149], v[230:231], v[152:153]
	v_pk_mul_f32 v[142:143], v[146:147], v[208:209]
	v_add_f32_dpp v154, v154, v154 quad_perm:[1,0,3,2] row_mask:0xf bank_mask:0xf bound_ctrl:1
	v_pk_mul_f32 v[144:145], v[148:149], v[216:217]
	v_add_f32_e32 v170, v152, v153
	v_add_f32_dpp v154, v154, v154 quad_perm:[2,3,0,1] row_mask:0xf bank_mask:0xf bound_ctrl:1
	v_pk_fma_f32 v[142:143], v[242:243], v[212:213], v[142:143] op_sel:[1,0,0] op_sel_hi:[1,1,1]
	v_pk_fma_f32 v[144:145], v[242:243], v[220:221], v[144:145] op_sel:[1,0,0] op_sel_hi:[1,1,1]
	v_add_f32_dpp v176, v168, v168 row_ror:8 row_mask:0xf bank_mask:0xc
	v_add_f32_dpp v154, v154, v154 row_half_mirror row_mask:0xf bank_mask:0xf bound_ctrl:1
	s_nop 1
	v_add_f32_dpp v177, v169, v169 row_ror:8 row_mask:0xf bank_mask:0xc
	v_add_f32_dpp v154, v154, v154 row_mirror row_mask:0xf bank_mask:0xf bound_ctrl:1
	v_pk_fma_f32 v[142:143], v[154:155], v[210:211], v[142:143] op_sel_hi:[0,1,1]
	v_pk_fma_f32 v[144:145], v[154:155], v[218:219], v[144:145] op_sel_hi:[0,1,1]
	v_pk_mul_f32 v[152:153], v[142:143], v[232:233]
	v_pk_fma_f32 v[152:153], v[144:145], v[234:235], v[152:153]
	s_nop 0
	v_add_f32_e32 v171, v152, v153
	v_add_f32_dpp v178, v170, v170 row_ror:8 row_mask:0xf bank_mask:0xc
	s_nop 0
	v_add_f32_dpp v179, v171, v171 row_ror:8 row_mask:0xf bank_mask:0xc
	s_nop 0
	v_add_f32_dpp v56, v172, v172 row_half_mirror row_mask:0xf bank_mask:0x5
	v_add_f32_dpp v57, v173, v173 row_half_mirror row_mask:0xf bank_mask:0x5
	v_add_f32_dpp v58, v174, v174 row_half_mirror row_mask:0xf bank_mask:0x5
	v_add_f32_dpp v59, v175, v175 row_half_mirror row_mask:0xf bank_mask:0x5
	v_add_f32_dpp v56, v176, v176 row_half_mirror row_mask:0xf bank_mask:0xa
	v_add_f32_dpp v57, v177, v177 row_half_mirror row_mask:0xf bank_mask:0xa
	v_add_f32_dpp v58, v178, v178 row_half_mirror row_mask:0xf bank_mask:0xa
	v_add_f32_dpp v59, v179, v179 row_half_mirror row_mask:0xf bank_mask:0xa
	v_cndmask_b32_e64 v178, v56, v58, s[14:15]
	v_cndmask_b32_e64 v176, v58, v56, s[14:15]
	v_cndmask_b32_e64 v179, v57, v59, s[14:15]
	v_cndmask_b32_e64 v177, v59, v57, s[14:15]
	s_nop 1
	v_add_f32_dpp v172, v176, v178 quad_perm:[2,3,0,1] row_mask:0xf bank_mask:0xf
	v_add_f32_dpp v173, v177, v179 quad_perm:[2,3,0,1] row_mask:0xf bank_mask:0xf
	v_cndmask_b32_e64 v176, v173, v172, s[16:17]
	v_cndmask_b32_e64 v178, v172, v173, s[16:17]
	s_nop 1
	v_add_f32_dpp v181, v176, v178 quad_perm:[1,0,3,2] row_mask:0xf bank_mask:0xf
	ds_write2st64_b32 v187, v180, v181 offset0:0 offset1:4

; __device__ __forceinline__ void wkv_phase(const WkvT& W, unsigned char* lds) {
;     ...
;                 const float* pp = sP + bo + jj * 12;
;                 const float* pv = sV + bi * 512 + il;
;                 f32x4 nA = *(const f32x4*)pp, nB = *(const f32x4*)(pp + 4); f32x2 nr = *(const f32x2*)(pp + 8); float nv = pv[0];
;                 float yk0 = 0.f, yk1 = 0.f, ep = 0.f;
;                 const bool oddrow = (lane & 16) != 0;
; #pragma unroll
;                 for (int t = 0; t < 32; ++t) {
;                     const f32x2 a2 = {nA[0], nA[1]}, w2 = {nA[2], nA[3]}, b2 = {nB[0], nB[1]}, k2 = {nB[2], nB[3]}, r2 = nr; const float v = nv;
;                     if (t + 1 < 32) { nA = *(const f32x4*)(pp + (t + 1) * 384); nB = *(const f32x4*)(pp + (t + 1) * 384 + 4); nr = *(const f32x2*)(pp + (t + 1) * 384 + 8); nv = pv[(t + 1) * 16]; }
;                     float S0 = S.x, S1 = S.y;
;                     float d = S0 * a2.x; d = __builtin_fmaf(S1, a2.y, d);
;                     float t0 = S0 * w2.x; t0 = __builtin_fmaf(v, k2.x, t0); asm volatile("" : "+v"(t0));
;                     float t1 = S1 * w2.y; t1 = __builtin_fmaf(v, k2.y, t1); asm volatile("" : "+v"(t1));
;                     float yprev; const float sa = wkv_reduce(d, ep, yprev);
;                     S0 = __builtin_fmaf(sa, b2.x, t0); asm volatile("" : "+v"(S0));
;                     S1 = __builtin_fmaf(sa, b2.y, t1); asm volatile("" : "+v"(S1));
;                     ep = S0 * r2.x; ep = __builtin_fmaf(S1, r2.y, ep);
;                     S.x = S0; S.y = S1;
;                     if (t >= 1) { const bool hit = oddrow && ((lane & 15) == ((t - 1) & 15)); if (t <= 16) yk0 = hit ? yprev : yk0; else yk1 = hit ? yprev : yk1; }
;                 }
.LBB0_1636:
	s_bitcmp1_b32 s99, 8
	s_cbranch_scc1 .Lwkv4_b2_skip
	ds_read_b128 v[190:193], v182 offset:49152
	ds_read_b128 v[194:197], v182 offset:49184
	ds_read_b128 v[198:201], v183 offset:49152
	ds_read_b128 v[202:205], v183 offset:49184
	ds_read_b128 v[228:231], v155 offset:49152
	ds_read2_b32 v[240:241], v226 offset0:0 offset1:16
	ds_read_b128 v[206:209], v182 offset:50688
	ds_read_b128 v[210:213], v182 offset:50720
	ds_read_b128 v[214:217], v183 offset:50688
	ds_read_b128 v[218:221], v183 offset:50720
	ds_read_b128 v[232:235], v155 offset:50688
	s_waitcnt lgkmcnt(5)
	v_pk_mul_f32 v[150:151], v[142:143], v[190:191]
	v_pk_fma_f32 v[150:151], v[144:145], v[198:199], v[150:151]
	v_pk_mul_f32 v[146:147], v[142:143], v[192:193]
	v_add_f32_e32 v154, v150, v151
	v_pk_mul_f32 v[148:149], v[144:145], v[200:201]
	v_pk_fma_f32 v[146:147], v[240:241], v[196:197], v[146:147] op_sel:[0,0,0] op_sel_hi:[0,1,1]
	v_add_f32_dpp v154, v154, v154 quad_perm:[1,0,3,2] row_mask:0xf bank_mask:0xf bound_ctrl:1
	v_pk_fma_f32 v[148:149], v[240:241], v[204:205], v[148:149] op_sel:[0,0,0] op_sel_hi:[0,1,1]
	s_nop 0
	v_add_f32_dpp v154, v154, v154 quad_perm:[2,3,0,1] row_mask:0xf bank_mask:0xf bound_ctrl:1
	ds_read_b128 v[126:129], v182 offset:52224
	ds_read_b128 v[130:133], v182 offset:52256
	v_add_f32_dpp v154, v154, v154 row_half_mirror row_mask:0xf bank_mask:0xf bound_ctrl:1
	ds_read_b128 v[134:137], v183 offset:52224
	ds_read_b128 v[222:225], v183 offset:52256
	v_add_f32_dpp v154, v154, v154 row_mirror row_mask:0xf bank_mask:0xf bound_ctrl:1
	v_pk_fma_f32 v[146:147], v[154:155], v[194:195], v[146:147] op_sel_hi:[0,1,1]
	v_pk_fma_f32 v[148:149], v[154:155], v[202:203], v[148:149] op_sel_hi:[0,1,1]
	ds_read_b128 v[236:239], v155 offset:52224
	ds_read2_b32 v[242:243], v226 offset0:32 offset1:48
	s_waitcnt lgkmcnt(6)
	v_pk_mul_f32 v[150:151], v[146:147], v[206:207]
	v_pk_fma_f32 v[150:151], v[148:149], v[214:215], v[150:151]
	v_pk_mul_f32 v[152:153], v[146:147], v[228:229]
	v_add_f32_e32 v154, v150, v151
	v_pk_fma_f32 v[152:153], v[148:149], v[230:231], v[152:153]
	v_pk_mul_f32 v[142:143], v[146:147], v[208:209]
	v_add_f32_dpp v154, v154, v154 quad_perm:[1,0,3,2] row_mask:0xf bank_mask:0xf bound_ctrl:1
	v_pk_mul_f32 v[144:145], v[148:149], v[216:217]
	v_add_f32_e32 v156, v152, v153
	v_add_f32_dpp v154, v154, v154 quad_perm:[2,3,0,1] row_mask:0xf bank_mask:0xf bound_ctrl:1
	v_pk_fma_f32 v[142:143], v[240:241], v[212:213], v[142:143] op_sel:[1,0,0] op_sel_hi:[1,1,1]
	v_pk_fma_f32 v[144:145], v[240:241], v[220:221], v[144:145] op_sel:[1,0,0] op_sel_hi:[1,1,1]
	v_add_f32_dpp v154, v154, v154 row_half_mirror row_mask:0xf bank_mask:0xf bound_ctrl:1
	ds_read_b128 v[190:193], v182 offset:53760
	ds_read_b128 v[194:197], v182 offset:53792
	v_add_f32_dpp v154, v154, v154 row_mirror row_mask:0xf bank_mask:0xf bound_ctrl:1
	v_pk_fma_f32 v[142:143], v[154:155], v[210:211], v[142:143] op_sel_hi:[0,1,1]
	v_pk_fma_f32 v[144:145], v[154:155], v[218:219], v[144:145] op_sel_hi:[0,1,1]
	ds_read_b128 v[198:201], v183 offset:53760
	ds_read_b128 v[202:205], v183 offset:53792
	ds_read_b128 v[228:231], v155 offset:53760
	s_waitcnt lgkmcnt(5)
	v_pk_mul_f32 v[150:151], v[142:143], v[126:127]
	v_pk_fma_f32 v[150:151], v[144:145], v[134:135], v[150:151]
	v_pk_mul_f32 v[152:153], v[142:143], v[232:233]
	v_add_f32_e32 v154, v150, v151
	v_pk_fma_f32 v[152:153], v[144:145], v[234:235], v[152:153]
	v_pk_mul_f32 v[146:147], v[142:143], v[128:129]
	v_add_f32_dpp v154, v154, v154 quad_perm:[1,0,3,2] row_mask:0xf bank_mask:0xf bound_ctrl:1
	v_pk_mul_f32 v[148:149], v[144:145], v[136:137]
	v_add_f32_e32 v157, v152, v153
	v_add_f32_dpp v154, v154, v154 quad_perm:[2,3,0,1] row_mask:0xf bank_mask:0xf bound_ctrl:1
	v_pk_fma_f32 v[146:147], v[242:243], v[132:133], v[146:147] op_sel:[0,0,0] op_sel_hi:[0,1,1]
	v_pk_fma_f32 v[148:149], v[242:243], v[224:225], v[148:149] op_sel:[0,0,0] op_sel_hi:[0,1,1]
	v_add_f32_dpp v154, v154, v154 row_half_mirror row_mask:0xf bank_mask:0xf bound_ctrl:1
	ds_read_b128 v[206:209], v182 offset:55296
	ds_read_b128 v[210:213], v182 offset:55328
	v_add_f32_dpp v154, v154, v154 row_mirror row_mask:0xf bank_mask:0xf bound_ctrl:1
	ds_read_b128 v[214:217], v183 offset:55296
	v_pk_fma_f32 v[146:147], v[154:155], v[130:131], v[146:147] op_sel_hi:[0,1,1]
	v_pk_fma_f32 v[148:149], v[154:155], v[222:223], v[148:149] op_sel_hi:[0,1,1]
	ds_read_b128 v[218:221], v183 offset:55328
	ds_read_b128 v[232:235], v155 offset:55296
	ds_read2_b32 v[240:241], v226 offset0:64 offset1:80
	s_waitcnt lgkmcnt(6)
	v_pk_mul_f32 v[150:151], v[146:147], v[190:191]
	v_pk_fma_f32 v[150:151], v[148:149], v[198:199], v[150:151]
	v_pk_mul_f32 v[152:153], v[146:147], v[236:237]
	v_add_f32_e32 v154, v150, v151
	v_pk_fma_f32 v[152:153], v[148:149], v[238:239], v[152:153]
	v_pk_mul_f32 v[142:143], v[146:147], v[192:193]
	v_add_f32_dpp v154, v154, v154 quad_perm:[1,0,3,2] row_mask:0xf bank_mask:0xf bound_ctrl:1
	v_pk_mul_f32 v[144:145], v[148:149], v[200:201]
	v_add_f32_e32 v158, v152, v153
	v_add_f32_dpp v154, v154, v154 quad_perm:[2,3,0,1] row_mask:0xf bank_mask:0xf bound_ctrl:1
	v_pk_fma_f32 v[142:143], v[242:243], v[196:197], v[142:143] op_sel:[1,0,0] op_sel_hi:[1,1,1]
	v_pk_fma_f32 v[144:145], v[242:243], v[204:205], v[144:145] op_sel:[1,0,0] op_sel_hi:[1,1,1]
	v_add_f32_dpp v154, v154, v154 row_half_mirror row_mask:0xf bank_mask:0xf bound_ctrl:1
	ds_read_b128 v[126:129], v182 offset:56832
	ds_read_b128 v[130:133], v182 offset:56864
	v_add_f32_dpp v154, v154, v154 row_mirror row_mask:0xf bank_mask:0xf bound_ctrl:1
	v_pk_fma_f32 v[142:143], v[154:155], v[194:195], v[142:143] op_sel_hi:[0,1,1]
	v_pk_fma_f32 v[144:145], v[154:155], v[202:203], v[144:145] op_sel_hi:[0,1,1]
	ds_read_b128 v[134:137], v183 offset:56832
	ds_read_b128 v[222:225], v183 offset:56864
	ds_read_b128 v[236:239], v155 offset:56832
	s_waitcnt lgkmcnt(5)
; __device__ __forceinline__ void wkv_phase(const WkvT& W, unsigned char* lds) {
;     ...
;                 for (int t = 0; t < 32; ++t) {
;                     const f32x2 a2 = {nA[0], nA[1]}, w2 = {nA[2], nA[3]}, b2 = {nB[0], nB[1]}, k2 = {nB[2], nB[3]}, r2 = nr; const float v = nv;
;                     if (t + 1 < 32) { nA = *(const f32x4*)(pp + (t + 1) * 384); nB = *(const f32x4*)(pp + (t + 1) * 384 + 4); nr = *(const f32x2*)(pp + (t + 1) * 384 + 8); nv = pv[(t + 1) * 16]; }
;                     float S0 = S.x, S1 = S.y;
;                     float d = S0 * a2.x; d = __builtin_fmaf(S1, a2.y, d);
;                     float t0 = S0 * w2.x; t0 = __builtin_fmaf(v, k2.x, t0); asm volatile("" : "+v"(t0));
;                     float t1 = S1 * w2.y; t1 = __builtin_fmaf(v, k2.y, t1); asm volatile("" : "+v"(t1));
;                     float yprev; const float sa = wkv_reduce(d, ep, yprev);
;                     S0 = __builtin_fmaf(sa, b2.x, t0); asm volatile("" : "+v"(S0));
;                     S1 = __builtin_fmaf(sa, b2.y, t1); asm volatile("" : "+v"(S1));
;                     ep = S0 * r2.x; ep = __builtin_fmaf(S1, r2.y, ep);
;                     S.x = S0; S.y = S1;
	v_pk_mul_f32 v[150:151], v[142:143], v[206:207]
	v_pk_fma_f32 v[150:151], v[144:145], v[214:215], v[150:151]
	v_pk_mul_f32 v[152:153], v[142:143], v[228:229]
	v_add_f32_e32 v154, v150, v151
	v_pk_fma_f32 v[152:153], v[144:145], v[230:231], v[152:153]
	v_pk_mul_f32 v[146:147], v[142:143], v[208:209]
	v_add_f32_dpp v154, v154, v154 quad_perm:[1,0,3,2] row_mask:0xf bank_mask:0xf bound_ctrl:1
	v_pk_mul_f32 v[148:149], v[144:145], v[216:217]
	v_add_f32_e32 v159, v152, v153
	v_add_f32_dpp v154, v154, v154 quad_perm:[2,3,0,1] row_mask:0xf bank_mask:0xf bound_ctrl:1
	v_pk_fma_f32 v[146:147], v[240:241], v[212:213], v[146:147] op_sel:[0,0,0] op_sel_hi:[0,1,1]
	v_pk_fma_f32 v[148:149], v[240:241], v[220:221], v[148:149] op_sel:[0,0,0] op_sel_hi:[0,1,1]
	v_add_f32_dpp v154, v154, v154 row_half_mirror row_mask:0xf bank_mask:0xf bound_ctrl:1
	ds_read_b128 v[190:193], v182 offset:58368
	ds_read_b128 v[194:197], v182 offset:58400
	v_add_f32_dpp v154, v154, v154 row_mirror row_mask:0xf bank_mask:0xf bound_ctrl:1
	ds_read_b128 v[198:201], v183 offset:58368
	v_pk_fma_f32 v[146:147], v[154:155], v[210:211], v[146:147] op_sel_hi:[0,1,1]
	v_pk_fma_f32 v[148:149], v[154:155], v[218:219], v[148:149] op_sel_hi:[0,1,1]
	ds_read_b128 v[202:205], v183 offset:58400
	ds_read_b128 v[228:231], v155 offset:58368
	ds_read2_b32 v[242:243], v226 offset0:96 offset1:112
	s_waitcnt lgkmcnt(6)
	v_pk_mul_f32 v[150:151], v[146:147], v[126:127]
	v_pk_fma_f32 v[150:151], v[148:149], v[134:135], v[150:151]
	v_pk_mul_f32 v[152:153], v[146:147], v[232:233]
	v_add_f32_e32 v154, v150, v151
	v_pk_fma_f32 v[152:153], v[148:149], v[234:235], v[152:153]
	v_pk_mul_f32 v[142:143], v[146:147], v[128:129]
	v_add_f32_dpp v154, v154, v154 quad_perm:[1,0,3,2] row_mask:0xf bank_mask:0xf bound_ctrl:1
	v_pk_mul_f32 v[144:145], v[148:149], v[136:137]
	v_add_f32_e32 v160, v152, v153
	v_add_f32_dpp v154, v154, v154 quad_perm:[2,3,0,1] row_mask:0xf bank_mask:0xf bound_ctrl:1
	v_pk_fma_f32 v[142:143], v[240:241], v[132:133], v[142:143] op_sel:[1,0,0] op_sel_hi:[1,1,1]
	v_pk_fma_f32 v[144:145], v[240:241], v[224:225], v[144:145] op_sel:[1,0,0] op_sel_hi:[1,1,1]
	v_add_f32_dpp v154, v154, v154 row_half_mirror row_mask:0xf bank_mask:0xf bound_ctrl:1
	ds_read_b128 v[206:209], v182 offset:59904
	ds_read_b128 v[210:213], v182 offset:59936
	v_add_f32_dpp v154, v154, v154 row_mirror row_mask:0xf bank_mask:0xf bound_ctrl:1
	v_pk_fma_f32 v[142:143], v[154:155], v[130:131], v[142:143] op_sel_hi:[0,1,1]
	v_pk_fma_f32 v[144:145], v[154:155], v[222:223], v[144:145] op_sel_hi:[0,1,1]
	ds_read_b128 v[214:217], v183 offset:59904
	ds_read_b128 v[218:221], v183 offset:59936
	ds_read_b128 v[232:235], v155 offset:59904
	s_waitcnt lgkmcnt(5)
	v_pk_mul_f32 v[150:151], v[142:143], v[190:191]
	v_pk_fma_f32 v[150:151], v[144:145], v[198:199], v[150:151]
	v_pk_mul_f32 v[152:153], v[142:143], v[236:237]
	v_add_f32_e32 v154, v150, v151
	v_pk_fma_f32 v[152:153], v[144:145], v[238:239], v[152:153]
	v_pk_mul_f32 v[146:147], v[142:143], v[192:193]
	v_add_f32_dpp v154, v154, v154 quad_perm:[1,0,3,2] row_mask:0xf bank_mask:0xf bound_ctrl:1
	v_pk_mul_f32 v[148:149], v[144:145], v[200:201]
	v_add_f32_e32 v161, v152, v153
	v_add_f32_dpp v154, v154, v154 quad_perm:[2,3,0,1] row_mask:0xf bank_mask:0xf bound_ctrl:1
	v_pk_fma_f32 v[146:147], v[242:243], v[196:197], v[146:147] op_sel:[0,0,0] op_sel_hi:[0,1,1]
	v_pk_fma_f32 v[148:149], v[242:243], v[204:205], v[148:149] op_sel:[0,0,0] op_sel_hi:[0,1,1]
	v_add_f32_dpp v154, v154, v154 row_half_mirror row_mask:0xf bank_mask:0xf bound_ctrl:1
	ds_read_b128 v[126:129], v182 offset:61440
	ds_read_b128 v[130:133], v182 offset:61472
	v_add_f32_dpp v154, v154, v154 row_mirror row_mask:0xf bank_mask:0xf bound_ctrl:1
	ds_read_b128 v[134:137], v183 offset:61440
	v_pk_fma_f32 v[146:147], v[154:155], v[194:195], v[146:147] op_sel_hi:[0,1,1]
	v_pk_fma_f32 v[148:149], v[154:155], v[202:203], v[148:149] op_sel_hi:[0,1,1]
	ds_read_b128 v[222:225], v183 offset:61472
	ds_read_b128 v[236:239], v155 offset:61440
	ds_read2_b32 v[240:241], v226 offset0:128 offset1:144
	s_waitcnt lgkmcnt(6)
	v_pk_mul_f32 v[150:151], v[146:147], v[206:207]
	v_pk_fma_f32 v[150:151], v[148:149], v[214:215], v[150:151]
	v_pk_mul_f32 v[152:153], v[146:147], v[228:229]
	v_add_f32_e32 v154, v150, v151
	v_pk_fma_f32 v[152:153], v[148:149], v[230:231], v[152:153]
	v_pk_mul_f32 v[142:143], v[146:147], v[208:209]
	v_add_f32_dpp v154, v154, v154 quad_perm:[1,0,3,2] row_mask:0xf bank_mask:0xf bound_ctrl:1
	v_pk_mul_f32 v[144:145], v[148:149], v[216:217]
	v_add_f32_e32 v162, v152, v153
	v_add_f32_dpp v154, v154, v154 quad_perm:[2,3,0,1] row_mask:0xf bank_mask:0xf bound_ctrl:1
	v_pk_fma_f32 v[142:143], v[242:243], v[212:213], v[142:143] op_sel:[1,0,0] op_sel_hi:[1,1,1]
	v_pk_fma_f32 v[144:145], v[242:243], v[220:221], v[144:145] op_sel:[1,0,0] op_sel_hi:[1,1,1]
	v_add_f32_dpp v154, v154, v154 row_half_mirror row_mask:0xf bank_mask:0xf bound_ctrl:1
	ds_read_b128 v[190:193], v182 offset:62976
	ds_read_b128 v[194:197], v182 offset:63008
	v_add_f32_dpp v154, v154, v154 row_mirror row_mask:0xf bank_mask:0xf bound_ctrl:1
	v_pk_fma_f32 v[142:143], v[154:155], v[210:211], v[142:143] op_sel_hi:[0,1,1]
	v_pk_fma_f32 v[144:145], v[154:155], v[218:219], v[144:145] op_sel_hi:[0,1,1]
	ds_read_b128 v[198:201], v183 offset:62976
	ds_read_b128 v[202:205], v183 offset:63008
	ds_read_b128 v[228:231], v155 offset:62976
	s_waitcnt lgkmcnt(5)
; __device__ __forceinline__ void wkv_phase(const WkvT& W, unsigned char* lds) {
;     ...
;                 for (int t = 0; t < 32; ++t) {
;                     const f32x2 a2 = {nA[0], nA[1]}, w2 = {nA[2], nA[3]}, b2 = {nB[0], nB[1]}, k2 = {nB[2], nB[3]}, r2 = nr; const float v = nv;
;                     if (t + 1 < 32) { nA = *(const f32x4*)(pp + (t + 1) * 384); nB = *(const f32x4*)(pp + (t + 1) * 384 + 4); nr = *(const f32x2*)(pp + (t + 1) * 384 + 8); nv = pv[(t + 1) * 16]; }
;                     float S0 = S.x, S1 = S.y;
;                     float d = S0 * a2.x; d = __builtin_fmaf(S1, a2.y, d);
;                     float t0 = S0 * w2.x; t0 = __builtin_fmaf(v, k2.x, t0); asm volatile("" : "+v"(t0));
;                     float t1 = S1 * w2.y; t1 = __builtin_fmaf(v, k2.y, t1); asm volatile("" : "+v"(t1));
;                     float yprev; const float sa = wkv_reduce(d, ep, yprev);
;                     S0 = __builtin_fmaf(sa, b2.x, t0); asm volatile("" : "+v"(S0));
;                     S1 = __builtin_fmaf(sa, b2.y, t1); asm volatile("" : "+v"(S1));
;                     ep = S0 * r2.x; ep = __builtin_fmaf(S1, r2.y, ep);
;                     S.x = S0; S.y = S1;
	v_pk_mul_f32 v[150:151], v[142:143], v[126:127]
	v_pk_fma_f32 v[150:151], v[144:145], v[134:135], v[150:151]
	v_pk_mul_f32 v[152:153], v[142:143], v[232:233]
	v_add_f32_e32 v154, v150, v151
	v_pk_fma_f32 v[152:153], v[144:145], v[234:235], v[152:153]
	v_pk_mul_f32 v[146:147], v[142:143], v[128:129]
	v_add_f32_dpp v154, v154, v154 quad_perm:[1,0,3,2] row_mask:0xf bank_mask:0xf bound_ctrl:1
	v_pk_mul_f32 v[148:149], v[144:145], v[136:137]
	v_add_f32_e32 v163, v152, v153
	v_add_f32_dpp v154, v154, v154 quad_perm:[2,3,0,1] row_mask:0xf bank_mask:0xf bound_ctrl:1
	v_pk_fma_f32 v[146:147], v[240:241], v[132:133], v[146:147] op_sel:[0,0,0] op_sel_hi:[0,1,1]
	v_pk_fma_f32 v[148:149], v[240:241], v[224:225], v[148:149] op_sel:[0,0,0] op_sel_hi:[0,1,1]
	v_add_f32_dpp v154, v154, v154 row_half_mirror row_mask:0xf bank_mask:0xf bound_ctrl:1
	ds_read_b128 v[206:209], v182 offset:64512
	ds_read_b128 v[210:213], v182 offset:64544
	v_add_f32_dpp v154, v154, v154 row_mirror row_mask:0xf bank_mask:0xf bound_ctrl:1
	ds_read_b128 v[214:217], v183 offset:64512
	v_pk_fma_f32 v[146:147], v[154:155], v[130:131], v[146:147] op_sel_hi:[0,1,1]
	v_pk_fma_f32 v[148:149], v[154:155], v[222:223], v[148:149] op_sel_hi:[0,1,1]
	ds_read_b128 v[218:221], v183 offset:64544
	ds_read_b128 v[232:235], v155 offset:64512
	ds_read2_b32 v[242:243], v226 offset0:160 offset1:176
	s_waitcnt lgkmcnt(6)
	v_pk_mul_f32 v[150:151], v[146:147], v[190:191]
	v_pk_fma_f32 v[150:151], v[148:149], v[198:199], v[150:151]
	v_pk_mul_f32 v[152:153], v[146:147], v[236:237]
	v_add_f32_e32 v154, v150, v151
	v_pk_fma_f32 v[152:153], v[148:149], v[238:239], v[152:153]
	v_pk_mul_f32 v[142:143], v[146:147], v[192:193]
	v_add_f32_dpp v154, v154, v154 quad_perm:[1,0,3,2] row_mask:0xf bank_mask:0xf bound_ctrl:1
	v_pk_mul_f32 v[144:145], v[148:149], v[200:201]
	v_add_f32_e32 v164, v152, v153
	v_add_f32_dpp v154, v154, v154 quad_perm:[2,3,0,1] row_mask:0xf bank_mask:0xf bound_ctrl:1
	v_pk_fma_f32 v[142:143], v[240:241], v[196:197], v[142:143] op_sel:[1,0,0] op_sel_hi:[1,1,1]
	v_pk_fma_f32 v[144:145], v[240:241], v[204:205], v[144:145] op_sel:[1,0,0] op_sel_hi:[1,1,1]
	v_add_f32_dpp v154, v154, v154 row_half_mirror row_mask:0xf bank_mask:0xf bound_ctrl:1
	ds_read_b128 v[126:129], v184
	ds_read_b128 v[130:133], v184 offset:32
	v_add_f32_dpp v154, v154, v154 row_mirror row_mask:0xf bank_mask:0xf bound_ctrl:1
	v_pk_fma_f32 v[142:143], v[154:155], v[194:195], v[142:143] op_sel_hi:[0,1,1]
	v_pk_fma_f32 v[144:145], v[154:155], v[202:203], v[144:145] op_sel_hi:[0,1,1]
	ds_read_b128 v[134:137], v185
	ds_read_b128 v[222:225], v185 offset:32
	ds_read_b128 v[236:239], v188
	s_waitcnt lgkmcnt(5)
	v_pk_mul_f32 v[150:151], v[142:143], v[206:207]
	v_pk_fma_f32 v[150:151], v[144:145], v[214:215], v[150:151]
	v_pk_mul_f32 v[152:153], v[142:143], v[228:229]
	v_add_f32_e32 v154, v150, v151
	v_pk_fma_f32 v[152:153], v[144:145], v[230:231], v[152:153]
	v_pk_mul_f32 v[146:147], v[142:143], v[208:209]
	v_add_f32_dpp v154, v154, v154 quad_perm:[1,0,3,2] row_mask:0xf bank_mask:0xf bound_ctrl:1
	v_pk_mul_f32 v[148:149], v[144:145], v[216:217]
	v_add_f32_e32 v165, v152, v153
	v_add_f32_dpp v154, v154, v154 quad_perm:[2,3,0,1] row_mask:0xf bank_mask:0xf bound_ctrl:1
	v_pk_fma_f32 v[146:147], v[242:243], v[212:213], v[146:147] op_sel:[0,0,0] op_sel_hi:[0,1,1]
	v_pk_fma_f32 v[148:149], v[242:243], v[220:221], v[148:149] op_sel:[0,0,0] op_sel_hi:[0,1,1]
	v_add_f32_dpp v154, v154, v154 row_half_mirror row_mask:0xf bank_mask:0xf bound_ctrl:1
	ds_read_b128 v[190:193], v184 offset:1536
	ds_read_b128 v[194:197], v184 offset:1568
	v_add_f32_dpp v154, v154, v154 row_mirror row_mask:0xf bank_mask:0xf bound_ctrl:1
	ds_read_b128 v[198:201], v185 offset:1536
	v_pk_fma_f32 v[146:147], v[154:155], v[210:211], v[146:147] op_sel_hi:[0,1,1]
	v_pk_fma_f32 v[148:149], v[154:155], v[218:219], v[148:149] op_sel_hi:[0,1,1]
	ds_read_b128 v[202:205], v185 offset:1568
	ds_read_b128 v[228:231], v188 offset:1536
	ds_read2_b32 v[240:241], v226 offset0:192 offset1:208
	s_waitcnt lgkmcnt(6)
	v_pk_mul_f32 v[150:151], v[146:147], v[126:127]
	v_pk_fma_f32 v[150:151], v[148:149], v[134:135], v[150:151]
	v_pk_mul_f32 v[152:153], v[146:147], v[232:233]
	v_add_f32_e32 v154, v150, v151
	v_pk_fma_f32 v[152:153], v[148:149], v[234:235], v[152:153]
	v_pk_mul_f32 v[142:143], v[146:147], v[128:129]
	v_add_f32_dpp v154, v154, v154 quad_perm:[1,0,3,2] row_mask:0xf bank_mask:0xf bound_ctrl:1
	v_pk_mul_f32 v[144:145], v[148:149], v[136:137]
	v_add_f32_e32 v166, v152, v153
	v_add_f32_dpp v154, v154, v154 quad_perm:[2,3,0,1] row_mask:0xf bank_mask:0xf bound_ctrl:1
	v_pk_fma_f32 v[142:143], v[242:243], v[132:133], v[142:143] op_sel:[1,0,0] op_sel_hi:[1,1,1]
	v_pk_fma_f32 v[144:145], v[242:243], v[224:225], v[144:145] op_sel:[1,0,0] op_sel_hi:[1,1,1]
	v_add_f32_dpp v154, v154, v154 row_half_mirror row_mask:0xf bank_mask:0xf bound_ctrl:1
	ds_read_b128 v[206:209], v184 offset:3072
	ds_read_b128 v[210:213], v184 offset:3104
	v_add_f32_dpp v154, v154, v154 row_mirror row_mask:0xf bank_mask:0xf bound_ctrl:1
	v_pk_fma_f32 v[142:143], v[154:155], v[130:131], v[142:143] op_sel_hi:[0,1,1]
	v_pk_fma_f32 v[144:145], v[154:155], v[222:223], v[144:145] op_sel_hi:[0,1,1]
	ds_read_b128 v[214:217], v185 offset:3072
	ds_read_b128 v[218:221], v185 offset:3104
	ds_read_b128 v[232:235], v188 offset:3072
	s_waitcnt lgkmcnt(5)
; __device__ __forceinline__ void wkv_phase(const WkvT& W, unsigned char* lds) {
;     ...
;                 for (int t = 0; t < 32; ++t) {
;                     const f32x2 a2 = {nA[0], nA[1]}, w2 = {nA[2], nA[3]}, b2 = {nB[0], nB[1]}, k2 = {nB[2], nB[3]}, r2 = nr; const float v = nv;
;                     if (t + 1 < 32) { nA = *(const f32x4*)(pp + (t + 1) * 384); nB = *(const f32x4*)(pp + (t + 1) * 384 + 4); nr = *(const f32x2*)(pp + (t + 1) * 384 + 8); nv = pv[(t + 1) * 16]; }
;                     float S0 = S.x, S1 = S.y;
;                     float d = S0 * a2.x; d = __builtin_fmaf(S1, a2.y, d);
;                     float t0 = S0 * w2.x; t0 = __builtin_fmaf(v, k2.x, t0); asm volatile("" : "+v"(t0));
;                     float t1 = S1 * w2.y; t1 = __builtin_fmaf(v, k2.y, t1); asm volatile("" : "+v"(t1));
;                     float yprev; const float sa = wkv_reduce(d, ep, yprev);
;                     S0 = __builtin_fmaf(sa, b2.x, t0); asm volatile("" : "+v"(S0));
;                     S1 = __builtin_fmaf(sa, b2.y, t1); asm volatile("" : "+v"(S1));
;                     ep = S0 * r2.x; ep = __builtin_fmaf(S1, r2.y, ep);
;                     S.x = S0; S.y = S1;
	v_pk_mul_f32 v[150:151], v[142:143], v[190:191]
	v_pk_fma_f32 v[150:151], v[144:145], v[198:199], v[150:151]
	v_pk_mul_f32 v[152:153], v[142:143], v[236:237]
	v_add_f32_e32 v154, v150, v151
	v_pk_fma_f32 v[152:153], v[144:145], v[238:239], v[152:153]
	v_pk_mul_f32 v[146:147], v[142:143], v[192:193]
	v_add_f32_dpp v154, v154, v154 quad_perm:[1,0,3,2] row_mask:0xf bank_mask:0xf bound_ctrl:1
	v_pk_mul_f32 v[148:149], v[144:145], v[200:201]
	v_add_f32_e32 v167, v152, v153
	v_add_f32_dpp v154, v154, v154 quad_perm:[2,3,0,1] row_mask:0xf bank_mask:0xf bound_ctrl:1
	v_pk_fma_f32 v[146:147], v[240:241], v[196:197], v[146:147] op_sel:[0,0,0] op_sel_hi:[0,1,1]
	v_pk_fma_f32 v[148:149], v[240:241], v[204:205], v[148:149] op_sel:[0,0,0] op_sel_hi:[0,1,1]
	v_add_f32_dpp v154, v154, v154 row_half_mirror row_mask:0xf bank_mask:0xf bound_ctrl:1
	ds_read_b128 v[126:129], v184 offset:4608
	ds_read_b128 v[130:133], v184 offset:4640
	v_add_f32_dpp v154, v154, v154 row_mirror row_mask:0xf bank_mask:0xf bound_ctrl:1
	ds_read_b128 v[134:137], v185 offset:4608
	v_pk_fma_f32 v[146:147], v[154:155], v[194:195], v[146:147] op_sel_hi:[0,1,1]
	v_pk_fma_f32 v[148:149], v[154:155], v[202:203], v[148:149] op_sel_hi:[0,1,1]
	ds_read_b128 v[222:225], v185 offset:4640
	ds_read_b128 v[236:239], v188 offset:4608
	ds_read2_b32 v[242:243], v226 offset0:224 offset1:240
	s_waitcnt lgkmcnt(6)
	v_pk_mul_f32 v[150:151], v[146:147], v[206:207]
	v_pk_fma_f32 v[150:151], v[148:149], v[214:215], v[150:151]
	v_pk_mul_f32 v[152:153], v[146:147], v[228:229]
	v_add_f32_e32 v154, v150, v151
	v_pk_fma_f32 v[152:153], v[148:149], v[230:231], v[152:153]
	v_pk_mul_f32 v[142:143], v[146:147], v[208:209]
	v_add_f32_dpp v154, v154, v154 quad_perm:[1,0,3,2] row_mask:0xf bank_mask:0xf bound_ctrl:1
	v_pk_mul_f32 v[144:145], v[148:149], v[216:217]
	v_add_f32_e32 v168, v152, v153
	v_add_f32_dpp v154, v154, v154 quad_perm:[2,3,0,1] row_mask:0xf bank_mask:0xf bound_ctrl:1
	v_pk_fma_f32 v[142:143], v[240:241], v[212:213], v[142:143] op_sel:[1,0,0] op_sel_hi:[1,1,1]
	v_pk_fma_f32 v[144:145], v[240:241], v[220:221], v[144:145] op_sel:[1,0,0] op_sel_hi:[1,1,1]
	v_add_f32_dpp v154, v154, v154 row_half_mirror row_mask:0xf bank_mask:0xf bound_ctrl:1
	ds_read_b128 v[190:193], v184 offset:6144
	ds_read_b128 v[194:197], v184 offset:6176
	v_add_f32_dpp v154, v154, v154 row_mirror row_mask:0xf bank_mask:0xf bound_ctrl:1
	v_pk_fma_f32 v[142:143], v[154:155], v[210:211], v[142:143] op_sel_hi:[0,1,1]
	v_pk_fma_f32 v[144:145], v[154:155], v[218:219], v[144:145] op_sel_hi:[0,1,1]
	ds_read_b128 v[198:201], v185 offset:6144
	ds_read_b128 v[202:205], v185 offset:6176
	ds_read_b128 v[228:231], v188 offset:6144
	s_waitcnt lgkmcnt(5)
	v_pk_mul_f32 v[150:151], v[142:143], v[126:127]
	v_pk_fma_f32 v[150:151], v[144:145], v[134:135], v[150:151]
	v_pk_mul_f32 v[152:153], v[142:143], v[232:233]
	v_add_f32_e32 v154, v150, v151
	v_pk_fma_f32 v[152:153], v[144:145], v[234:235], v[152:153]
	v_pk_mul_f32 v[146:147], v[142:143], v[128:129]
	v_add_f32_dpp v154, v154, v154 quad_perm:[1,0,3,2] row_mask:0xf bank_mask:0xf bound_ctrl:1
	v_pk_mul_f32 v[148:149], v[144:145], v[136:137]
	v_add_f32_e32 v169, v152, v153
	v_add_f32_dpp v154, v154, v154 quad_perm:[2,3,0,1] row_mask:0xf bank_mask:0xf bound_ctrl:1
	v_pk_fma_f32 v[146:147], v[242:243], v[132:133], v[146:147] op_sel:[0,0,0] op_sel_hi:[0,1,1]
	v_pk_fma_f32 v[148:149], v[242:243], v[224:225], v[148:149] op_sel:[0,0,0] op_sel_hi:[0,1,1]
	v_add_f32_dpp v154, v154, v154 row_half_mirror row_mask:0xf bank_mask:0xf bound_ctrl:1
	ds_read_b128 v[206:209], v184 offset:7680
	ds_read_b128 v[210:213], v184 offset:7712
	v_add_f32_dpp v154, v154, v154 row_mirror row_mask:0xf bank_mask:0xf bound_ctrl:1
	ds_read_b128 v[214:217], v185 offset:7680
	v_pk_fma_f32 v[146:147], v[154:155], v[130:131], v[146:147] op_sel_hi:[0,1,1]
	v_pk_fma_f32 v[148:149], v[154:155], v[222:223], v[148:149] op_sel_hi:[0,1,1]
	ds_read_b128 v[218:221], v185 offset:7712
	ds_read_b128 v[232:235], v188 offset:7680
	ds_read2_b32 v[240:241], v227 offset0:0 offset1:16
	s_waitcnt lgkmcnt(6)
	v_pk_mul_f32 v[150:151], v[146:147], v[190:191]
	v_pk_fma_f32 v[150:151], v[148:149], v[198:199], v[150:151]
	v_pk_mul_f32 v[152:153], v[146:147], v[236:237]
	v_add_f32_e32 v154, v150, v151
	v_pk_fma_f32 v[152:153], v[148:149], v[238:239], v[152:153]
	v_pk_mul_f32 v[142:143], v[146:147], v[192:193]
	v_add_f32_dpp v154, v154, v154 quad_perm:[1,0,3,2] row_mask:0xf bank_mask:0xf bound_ctrl:1
	v_pk_mul_f32 v[144:145], v[148:149], v[200:201]
	v_add_f32_e32 v170, v152, v153
	v_add_f32_dpp v154, v154, v154 quad_perm:[2,3,0,1] row_mask:0xf bank_mask:0xf bound_ctrl:1
	v_pk_fma_f32 v[142:143], v[242:243], v[196:197], v[142:143] op_sel:[1,0,0] op_sel_hi:[1,1,1]
	v_pk_fma_f32 v[144:145], v[242:243], v[204:205], v[144:145] op_sel:[1,0,0] op_sel_hi:[1,1,1]
	v_add_f32_dpp v154, v154, v154 row_half_mirror row_mask:0xf bank_mask:0xf bound_ctrl:1
	ds_read_b128 v[126:129], v184 offset:9216
	ds_read_b128 v[130:133], v184 offset:9248
	v_add_f32_dpp v154, v154, v154 row_mirror row_mask:0xf bank_mask:0xf bound_ctrl:1
	v_pk_fma_f32 v[142:143], v[154:155], v[194:195], v[142:143] op_sel_hi:[0,1,1]
	v_pk_fma_f32 v[144:145], v[154:155], v[202:203], v[144:145] op_sel_hi:[0,1,1]
	ds_read_b128 v[134:137], v185 offset:9216
	ds_read_b128 v[222:225], v185 offset:9248
	ds_read_b128 v[236:239], v188 offset:9216
	s_waitcnt lgkmcnt(5)
; __device__ __forceinline__ void wkv_phase(const WkvT& W, unsigned char* lds) {
;     ...
;                 for (int t = 0; t < 32; ++t) {
;                     const f32x2 a2 = {nA[0], nA[1]}, w2 = {nA[2], nA[3]}, b2 = {nB[0], nB[1]}, k2 = {nB[2], nB[3]}, r2 = nr; const float v = nv;
;                     if (t + 1 < 32) { nA = *(const f32x4*)(pp + (t + 1) * 384); nB = *(const f32x4*)(pp + (t + 1) * 384 + 4); nr = *(const f32x2*)(pp + (t + 1) * 384 + 8); nv = pv[(t + 1) * 16]; }
;                     float S0 = S.x, S1 = S.y;
;                     float d = S0 * a2.x; d = __builtin_fmaf(S1, a2.y, d);
;                     float t0 = S0 * w2.x; t0 = __builtin_fmaf(v, k2.x, t0); asm volatile("" : "+v"(t0));
;                     float t1 = S1 * w2.y; t1 = __builtin_fmaf(v, k2.y, t1); asm volatile("" : "+v"(t1));
;                     float yprev; const float sa = wkv_reduce(d, ep, yprev);
;                     S0 = __builtin_fmaf(sa, b2.x, t0); asm volatile("" : "+v"(S0));
;                     S1 = __builtin_fmaf(sa, b2.y, t1); asm volatile("" : "+v"(S1));
;                     ep = S0 * r2.x; ep = __builtin_fmaf(S1, r2.y, ep);
;                     S.x = S0; S.y = S1;
;                     if (t >= 1) { const bool hit = oddrow && ((lane & 15) == ((t - 1) & 15)); if (t <= 16) yk0 = hit ? yprev : yk0; else yk1 = hit ? yprev : yk1; }
	v_pk_mul_f32 v[150:151], v[142:143], v[206:207]
	v_pk_fma_f32 v[150:151], v[144:145], v[214:215], v[150:151]
	v_pk_mul_f32 v[152:153], v[142:143], v[228:229]
	v_add_f32_e32 v154, v150, v151
	v_pk_fma_f32 v[152:153], v[144:145], v[230:231], v[152:153]
	v_pk_mul_f32 v[146:147], v[142:143], v[208:209]
	v_add_f32_dpp v154, v154, v154 quad_perm:[1,0,3,2] row_mask:0xf bank_mask:0xf bound_ctrl:1
	v_pk_mul_f32 v[148:149], v[144:145], v[216:217]
	v_add_f32_e32 v171, v152, v153
	v_add_f32_dpp v154, v154, v154 quad_perm:[2,3,0,1] row_mask:0xf bank_mask:0xf bound_ctrl:1
	v_pk_fma_f32 v[146:147], v[240:241], v[212:213], v[146:147] op_sel:[0,0,0] op_sel_hi:[0,1,1]
	v_pk_fma_f32 v[148:149], v[240:241], v[220:221], v[148:149] op_sel:[0,0,0] op_sel_hi:[0,1,1]
	v_add_f32_dpp v172, v156, v156 row_ror:8 row_mask:0xf bank_mask:0x3
	v_add_f32_dpp v154, v154, v154 row_half_mirror row_mask:0xf bank_mask:0xf bound_ctrl:1
	ds_read_b128 v[190:193], v184 offset:10752
	ds_read_b128 v[194:197], v184 offset:10784
	v_add_f32_dpp v173, v157, v157 row_ror:8 row_mask:0xf bank_mask:0x3
	v_add_f32_dpp v154, v154, v154 row_mirror row_mask:0xf bank_mask:0xf bound_ctrl:1
	ds_read_b128 v[198:201], v185 offset:10752
	v_pk_fma_f32 v[146:147], v[154:155], v[210:211], v[146:147] op_sel_hi:[0,1,1]
	v_pk_fma_f32 v[148:149], v[154:155], v[218:219], v[148:149] op_sel_hi:[0,1,1]
	v_add_f32_dpp v174, v158, v158 row_ror:8 row_mask:0xf bank_mask:0x3
	ds_read_b128 v[202:205], v185 offset:10784
	ds_read_b128 v[228:231], v188 offset:10752
	ds_read2_b32 v[242:243], v227 offset0:32 offset1:48
	v_add_f32_dpp v175, v159, v159 row_ror:8 row_mask:0xf bank_mask:0x3
	s_waitcnt lgkmcnt(6)
	v_pk_mul_f32 v[150:151], v[146:147], v[126:127]
	v_pk_fma_f32 v[150:151], v[148:149], v[134:135], v[150:151]
	v_pk_mul_f32 v[152:153], v[146:147], v[232:233]
	v_add_f32_e32 v154, v150, v151
	v_pk_fma_f32 v[152:153], v[148:149], v[234:235], v[152:153]
	v_pk_mul_f32 v[142:143], v[146:147], v[128:129]
	v_add_f32_dpp v154, v154, v154 quad_perm:[1,0,3,2] row_mask:0xf bank_mask:0xf bound_ctrl:1
	v_pk_mul_f32 v[144:145], v[148:149], v[136:137]
	v_add_f32_e32 v156, v152, v153
	v_add_f32_dpp v154, v154, v154 quad_perm:[2,3,0,1] row_mask:0xf bank_mask:0xf bound_ctrl:1
	v_pk_fma_f32 v[142:143], v[240:241], v[132:133], v[142:143] op_sel:[1,0,0] op_sel_hi:[1,1,1]
	v_pk_fma_f32 v[144:145], v[240:241], v[224:225], v[144:145] op_sel:[1,0,0] op_sel_hi:[1,1,1]
	v_add_f32_dpp v176, v160, v160 row_ror:8 row_mask:0xf bank_mask:0x3
	v_add_f32_dpp v154, v154, v154 row_half_mirror row_mask:0xf bank_mask:0xf bound_ctrl:1
	ds_read_b128 v[206:209], v184 offset:12288
	ds_read_b128 v[210:213], v184 offset:12320
	v_add_f32_dpp v177, v161, v161 row_ror:8 row_mask:0xf bank_mask:0x3
	v_add_f32_dpp v154, v154, v154 row_mirror row_mask:0xf bank_mask:0xf bound_ctrl:1
	v_pk_fma_f32 v[142:143], v[154:155], v[130:131], v[142:143] op_sel_hi:[0,1,1]
	v_pk_fma_f32 v[144:145], v[154:155], v[222:223], v[144:145] op_sel_hi:[0,1,1]
	v_add_f32_dpp v178, v162, v162 row_ror:8 row_mask:0xf bank_mask:0x3
	ds_read_b128 v[214:217], v185 offset:12288
	ds_read_b128 v[218:221], v185 offset:12320
	ds_read_b128 v[232:235], v188 offset:12288
	v_add_f32_dpp v179, v163, v163 row_ror:8 row_mask:0xf bank_mask:0x3
	s_waitcnt lgkmcnt(5)
	v_pk_mul_f32 v[150:151], v[142:143], v[190:191]
	v_pk_fma_f32 v[150:151], v[144:145], v[198:199], v[150:151]
	v_pk_mul_f32 v[152:153], v[142:143], v[236:237]
	v_add_f32_e32 v154, v150, v151
	v_pk_fma_f32 v[152:153], v[144:145], v[238:239], v[152:153]
	v_pk_mul_f32 v[146:147], v[142:143], v[192:193]
	v_add_f32_dpp v154, v154, v154 quad_perm:[1,0,3,2] row_mask:0xf bank_mask:0xf bound_ctrl:1
	v_pk_mul_f32 v[148:149], v[144:145], v[200:201]
	v_add_f32_e32 v157, v152, v153
	v_add_f32_dpp v154, v154, v154 quad_perm:[2,3,0,1] row_mask:0xf bank_mask:0xf bound_ctrl:1
	v_pk_fma_f32 v[146:147], v[242:243], v[196:197], v[146:147] op_sel:[0,0,0] op_sel_hi:[0,1,1]
	v_pk_fma_f32 v[148:149], v[242:243], v[204:205], v[148:149] op_sel:[0,0,0] op_sel_hi:[0,1,1]
	v_add_f32_dpp v172, v164, v164 row_ror:8 row_mask:0xf bank_mask:0xc
	v_add_f32_dpp v154, v154, v154 row_half_mirror row_mask:0xf bank_mask:0xf bound_ctrl:1
	ds_read_b128 v[126:129], v184 offset:13824
	ds_read_b128 v[130:133], v184 offset:13856
	v_add_f32_dpp v173, v165, v165 row_ror:8 row_mask:0xf bank_mask:0xc
	v_add_f32_dpp v154, v154, v154 row_mirror row_mask:0xf bank_mask:0xf bound_ctrl:1
	ds_read_b128 v[134:137], v185 offset:13824
	v_pk_fma_f32 v[146:147], v[154:155], v[194:195], v[146:147] op_sel_hi:[0,1,1]
	v_pk_fma_f32 v[148:149], v[154:155], v[202:203], v[148:149] op_sel_hi:[0,1,1]
	v_add_f32_dpp v174, v166, v166 row_ror:8 row_mask:0xf bank_mask:0xc
	ds_read_b128 v[222:225], v185 offset:13856
	ds_read_b128 v[236:239], v188 offset:13824
	ds_read2_b32 v[240:241], v227 offset0:64 offset1:80
	v_add_f32_dpp v175, v167, v167 row_ror:8 row_mask:0xf bank_mask:0xc
	s_waitcnt lgkmcnt(6)
; __device__ __forceinline__ void wkv_phase(const WkvT& W, unsigned char* lds) {
;     ...
;                 for (int t = 0; t < 32; ++t) {
;                     const f32x2 a2 = {nA[0], nA[1]}, w2 = {nA[2], nA[3]}, b2 = {nB[0], nB[1]}, k2 = {nB[2], nB[3]}, r2 = nr; const float v = nv;
;                     if (t + 1 < 32) { nA = *(const f32x4*)(pp + (t + 1) * 384); nB = *(const f32x4*)(pp + (t + 1) * 384 + 4); nr = *(const f32x2*)(pp + (t + 1) * 384 + 8); nv = pv[(t + 1) * 16]; }
;                     float S0 = S.x, S1 = S.y;
;                     float d = S0 * a2.x; d = __builtin_fmaf(S1, a2.y, d);
;                     float t0 = S0 * w2.x; t0 = __builtin_fmaf(v, k2.x, t0); asm volatile("" : "+v"(t0));
;                     float t1 = S1 * w2.y; t1 = __builtin_fmaf(v, k2.y, t1); asm volatile("" : "+v"(t1));
;                     float yprev; const float sa = wkv_reduce(d, ep, yprev);
;                     S0 = __builtin_fmaf(sa, b2.x, t0); asm volatile("" : "+v"(S0));
;                     S1 = __builtin_fmaf(sa, b2.y, t1); asm volatile("" : "+v"(S1));
;                     ep = S0 * r2.x; ep = __builtin_fmaf(S1, r2.y, ep);
;                     S.x = S0; S.y = S1;
;                     if (t >= 1) { const bool hit = oddrow && ((lane & 15) == ((t - 1) & 15)); if (t <= 16) yk0 = hit ? yprev : yk0; else yk1 = hit ? yprev : yk1; }
	v_pk_mul_f32 v[150:151], v[146:147], v[206:207]
	v_pk_fma_f32 v[150:151], v[148:149], v[214:215], v[150:151]
	v_pk_mul_f32 v[152:153], v[146:147], v[228:229]
	v_add_f32_e32 v154, v150, v151
	v_pk_fma_f32 v[152:153], v[148:149], v[230:231], v[152:153]
	v_pk_mul_f32 v[142:143], v[146:147], v[208:209]
	v_add_f32_dpp v154, v154, v154 quad_perm:[1,0,3,2] row_mask:0xf bank_mask:0xf bound_ctrl:1
	v_pk_mul_f32 v[144:145], v[148:149], v[216:217]
	v_add_f32_e32 v158, v152, v153
	v_add_f32_dpp v154, v154, v154 quad_perm:[2,3,0,1] row_mask:0xf bank_mask:0xf bound_ctrl:1
	v_pk_fma_f32 v[142:143], v[242:243], v[212:213], v[142:143] op_sel:[1,0,0] op_sel_hi:[1,1,1]
	v_pk_fma_f32 v[144:145], v[242:243], v[220:221], v[144:145] op_sel:[1,0,0] op_sel_hi:[1,1,1]
	v_add_f32_dpp v176, v168, v168 row_ror:8 row_mask:0xf bank_mask:0xc
	v_add_f32_dpp v154, v154, v154 row_half_mirror row_mask:0xf bank_mask:0xf bound_ctrl:1
	ds_read_b128 v[190:193], v184 offset:15360
	ds_read_b128 v[194:197], v184 offset:15392
	v_add_f32_dpp v177, v169, v169 row_ror:8 row_mask:0xf bank_mask:0xc
	v_add_f32_dpp v154, v154, v154 row_mirror row_mask:0xf bank_mask:0xf bound_ctrl:1
	v_pk_fma_f32 v[142:143], v[154:155], v[210:211], v[142:143] op_sel_hi:[0,1,1]
	v_pk_fma_f32 v[144:145], v[154:155], v[218:219], v[144:145] op_sel_hi:[0,1,1]
	v_add_f32_dpp v178, v170, v170 row_ror:8 row_mask:0xf bank_mask:0xc
	ds_read_b128 v[198:201], v185 offset:15360
	ds_read_b128 v[202:205], v185 offset:15392
	ds_read_b128 v[228:231], v188 offset:15360
	v_add_f32_dpp v179, v171, v171 row_ror:8 row_mask:0xf bank_mask:0xc
	s_waitcnt lgkmcnt(5)
	v_pk_mul_f32 v[150:151], v[142:143], v[126:127]
	v_pk_fma_f32 v[150:151], v[144:145], v[134:135], v[150:151]
	v_pk_mul_f32 v[152:153], v[142:143], v[232:233]
	v_add_f32_e32 v154, v150, v151
	v_pk_fma_f32 v[152:153], v[144:145], v[234:235], v[152:153]
	v_pk_mul_f32 v[146:147], v[142:143], v[128:129]
	v_add_f32_dpp v154, v154, v154 quad_perm:[1,0,3,2] row_mask:0xf bank_mask:0xf bound_ctrl:1
	v_pk_mul_f32 v[148:149], v[144:145], v[136:137]
	v_add_f32_e32 v159, v152, v153
	v_add_f32_dpp v154, v154, v154 quad_perm:[2,3,0,1] row_mask:0xf bank_mask:0xf bound_ctrl:1
	v_pk_fma_f32 v[146:147], v[240:241], v[132:133], v[146:147] op_sel:[0,0,0] op_sel_hi:[0,1,1]
	v_pk_fma_f32 v[148:149], v[240:241], v[224:225], v[148:149] op_sel:[0,0,0] op_sel_hi:[0,1,1]
	v_add_f32_dpp v56, v172, v172 row_half_mirror row_mask:0xf bank_mask:0x5
	v_add_f32_dpp v154, v154, v154 row_half_mirror row_mask:0xf bank_mask:0xf bound_ctrl:1
	ds_read_b128 v[206:209], v184 offset:16896
	ds_read_b128 v[210:213], v184 offset:16928
	v_add_f32_dpp v57, v173, v173 row_half_mirror row_mask:0xf bank_mask:0x5
	v_add_f32_dpp v154, v154, v154 row_mirror row_mask:0xf bank_mask:0xf bound_ctrl:1
	ds_read_b128 v[214:217], v185 offset:16896
	v_pk_fma_f32 v[146:147], v[154:155], v[130:131], v[146:147] op_sel_hi:[0,1,1]
	v_pk_fma_f32 v[148:149], v[154:155], v[222:223], v[148:149] op_sel_hi:[0,1,1]
	v_add_f32_dpp v58, v174, v174 row_half_mirror row_mask:0xf bank_mask:0x5
	ds_read_b128 v[218:221], v185 offset:16928
	ds_read_b128 v[232:235], v188 offset:16896
	ds_read2_b32 v[242:243], v227 offset0:96 offset1:112
	v_add_f32_dpp v59, v175, v175 row_half_mirror row_mask:0xf bank_mask:0x5
	s_waitcnt lgkmcnt(6)
	v_pk_mul_f32 v[150:151], v[146:147], v[190:191]
	v_pk_fma_f32 v[150:151], v[148:149], v[198:199], v[150:151]
	v_pk_mul_f32 v[152:153], v[146:147], v[236:237]
	v_add_f32_e32 v154, v150, v151
	v_pk_fma_f32 v[152:153], v[148:149], v[238:239], v[152:153]
	v_pk_mul_f32 v[142:143], v[146:147], v[192:193]
	v_add_f32_dpp v154, v154, v154 quad_perm:[1,0,3,2] row_mask:0xf bank_mask:0xf bound_ctrl:1
	v_pk_mul_f32 v[144:145], v[148:149], v[200:201]
	v_add_f32_e32 v160, v152, v153
	v_add_f32_dpp v154, v154, v154 quad_perm:[2,3,0,1] row_mask:0xf bank_mask:0xf bound_ctrl:1
	v_pk_fma_f32 v[142:143], v[240:241], v[196:197], v[142:143] op_sel:[1,0,0] op_sel_hi:[1,1,1]
	v_pk_fma_f32 v[144:145], v[240:241], v[204:205], v[144:145] op_sel:[1,0,0] op_sel_hi:[1,1,1]
	v_add_f32_dpp v56, v176, v176 row_half_mirror row_mask:0xf bank_mask:0xa
	v_add_f32_dpp v154, v154, v154 row_half_mirror row_mask:0xf bank_mask:0xf bound_ctrl:1
	ds_read_b128 v[126:129], v184 offset:18432
	ds_read_b128 v[130:133], v184 offset:18464
	v_add_f32_dpp v57, v177, v177 row_half_mirror row_mask:0xf bank_mask:0xa
	v_add_f32_dpp v154, v154, v154 row_mirror row_mask:0xf bank_mask:0xf bound_ctrl:1
	v_pk_fma_f32 v[142:143], v[154:155], v[194:195], v[142:143] op_sel_hi:[0,1,1]
	v_pk_fma_f32 v[144:145], v[154:155], v[202:203], v[144:145] op_sel_hi:[0,1,1]
	v_add_f32_dpp v58, v178, v178 row_half_mirror row_mask:0xf bank_mask:0xa
	ds_read_b128 v[134:137], v185 offset:18432
	ds_read_b128 v[222:225], v185 offset:18464
	ds_read_b128 v[236:239], v188 offset:18432
	v_add_f32_dpp v59, v179, v179 row_half_mirror row_mask:0xf bank_mask:0xa
	s_waitcnt lgkmcnt(5)
; __device__ __forceinline__ void wkv_phase(const WkvT& W, unsigned char* lds) {
;     ...
;                 for (int t = 0; t < 32; ++t) {
;                     const f32x2 a2 = {nA[0], nA[1]}, w2 = {nA[2], nA[3]}, b2 = {nB[0], nB[1]}, k2 = {nB[2], nB[3]}, r2 = nr; const float v = nv;
;                     if (t + 1 < 32) { nA = *(const f32x4*)(pp + (t + 1) * 384); nB = *(const f32x4*)(pp + (t + 1) * 384 + 4); nr = *(const f32x2*)(pp + (t + 1) * 384 + 8); nv = pv[(t + 1) * 16]; }
;                     float S0 = S.x, S1 = S.y;
;                     float d = S0 * a2.x; d = __builtin_fmaf(S1, a2.y, d);
;                     float t0 = S0 * w2.x; t0 = __builtin_fmaf(v, k2.x, t0); asm volatile("" : "+v"(t0));
;                     float t1 = S1 * w2.y; t1 = __builtin_fmaf(v, k2.y, t1); asm volatile("" : "+v"(t1));
;                     float yprev; const float sa = wkv_reduce(d, ep, yprev);
;                     S0 = __builtin_fmaf(sa, b2.x, t0); asm volatile("" : "+v"(S0));
;                     S1 = __builtin_fmaf(sa, b2.y, t1); asm volatile("" : "+v"(S1));
;                     ep = S0 * r2.x; ep = __builtin_fmaf(S1, r2.y, ep);
;                     S.x = S0; S.y = S1;
;                     if (t >= 1) { const bool hit = oddrow && ((lane & 15) == ((t - 1) & 15)); if (t <= 16) yk0 = hit ? yprev : yk0; else yk1 = hit ? yprev : yk1; }
	v_pk_mul_f32 v[150:151], v[142:143], v[206:207]
	v_pk_fma_f32 v[150:151], v[144:145], v[214:215], v[150:151]
	v_pk_mul_f32 v[152:153], v[142:143], v[228:229]
	v_add_f32_e32 v154, v150, v151
	v_pk_fma_f32 v[152:153], v[144:145], v[230:231], v[152:153]
	v_pk_mul_f32 v[146:147], v[142:143], v[208:209]
	v_add_f32_dpp v154, v154, v154 quad_perm:[1,0,3,2] row_mask:0xf bank_mask:0xf bound_ctrl:1
	v_pk_mul_f32 v[148:149], v[144:145], v[216:217]
	v_add_f32_e32 v161, v152, v153
	v_add_f32_dpp v154, v154, v154 quad_perm:[2,3,0,1] row_mask:0xf bank_mask:0xf bound_ctrl:1
	v_pk_fma_f32 v[146:147], v[242:243], v[212:213], v[146:147] op_sel:[0,0,0] op_sel_hi:[0,1,1]
	v_pk_fma_f32 v[148:149], v[242:243], v[220:221], v[148:149] op_sel:[0,0,0] op_sel_hi:[0,1,1]
	v_cndmask_b32_e64 v178, v56, v58, s[14:15]
	v_add_f32_dpp v154, v154, v154 row_half_mirror row_mask:0xf bank_mask:0xf bound_ctrl:1
	ds_read_b128 v[190:193], v184 offset:19968
	ds_read_b128 v[194:197], v184 offset:20000
	v_cndmask_b32_e64 v176, v58, v56, s[14:15]
	v_add_f32_dpp v154, v154, v154 row_mirror row_mask:0xf bank_mask:0xf bound_ctrl:1
	ds_read_b128 v[198:201], v185 offset:19968
	v_pk_fma_f32 v[146:147], v[154:155], v[210:211], v[146:147] op_sel_hi:[0,1,1]
	v_pk_fma_f32 v[148:149], v[154:155], v[218:219], v[148:149] op_sel_hi:[0,1,1]
	v_cndmask_b32_e64 v179, v57, v59, s[14:15]
	ds_read_b128 v[202:205], v185 offset:20000
	ds_read_b128 v[228:231], v188 offset:19968
	ds_read2_b32 v[240:241], v227 offset0:128 offset1:144
	v_cndmask_b32_e64 v177, v59, v57, s[14:15]
	s_waitcnt lgkmcnt(6)
	v_pk_mul_f32 v[150:151], v[146:147], v[126:127]
	v_pk_fma_f32 v[150:151], v[148:149], v[134:135], v[150:151]
	v_pk_mul_f32 v[152:153], v[146:147], v[232:233]
	v_add_f32_e32 v154, v150, v151
	v_pk_fma_f32 v[152:153], v[148:149], v[234:235], v[152:153]
	v_pk_mul_f32 v[142:143], v[146:147], v[128:129]
	v_add_f32_dpp v154, v154, v154 quad_perm:[1,0,3,2] row_mask:0xf bank_mask:0xf bound_ctrl:1
	v_pk_mul_f32 v[144:145], v[148:149], v[136:137]
	v_add_f32_e32 v162, v152, v153
	v_add_f32_dpp v154, v154, v154 quad_perm:[2,3,0,1] row_mask:0xf bank_mask:0xf bound_ctrl:1
	v_pk_fma_f32 v[142:143], v[242:243], v[132:133], v[142:143] op_sel:[1,0,0] op_sel_hi:[1,1,1]
	v_pk_fma_f32 v[144:145], v[242:243], v[224:225], v[144:145] op_sel:[1,0,0] op_sel_hi:[1,1,1]
	v_add_f32_dpp v172, v176, v178 quad_perm:[2,3,0,1] row_mask:0xf bank_mask:0xf
	v_add_f32_dpp v154, v154, v154 row_half_mirror row_mask:0xf bank_mask:0xf bound_ctrl:1
	ds_read_b128 v[206:209], v184 offset:21504
	ds_read_b128 v[210:213], v184 offset:21536
	v_add_f32_dpp v173, v177, v179 quad_perm:[2,3,0,1] row_mask:0xf bank_mask:0xf
	v_add_f32_dpp v154, v154, v154 row_mirror row_mask:0xf bank_mask:0xf bound_ctrl:1
	v_pk_fma_f32 v[142:143], v[154:155], v[130:131], v[142:143] op_sel_hi:[0,1,1]
	v_pk_fma_f32 v[144:145], v[154:155], v[222:223], v[144:145] op_sel_hi:[0,1,1]
	v_cndmask_b32_e64 v176, v173, v172, s[16:17]
	ds_read_b128 v[214:217], v185 offset:21504
	ds_read_b128 v[218:221], v185 offset:21536
	ds_read_b128 v[232:235], v188 offset:21504
	v_cndmask_b32_e64 v178, v172, v173, s[16:17]
	s_waitcnt lgkmcnt(5)
	v_pk_mul_f32 v[150:151], v[142:143], v[190:191]
	v_pk_fma_f32 v[150:151], v[144:145], v[198:199], v[150:151]
	v_pk_mul_f32 v[152:153], v[142:143], v[236:237]
	v_add_f32_e32 v154, v150, v151
	v_pk_fma_f32 v[152:153], v[144:145], v[238:239], v[152:153]
	v_pk_mul_f32 v[146:147], v[142:143], v[192:193]
	v_add_f32_dpp v154, v154, v154 quad_perm:[1,0,3,2] row_mask:0xf bank_mask:0xf bound_ctrl:1
	v_pk_mul_f32 v[148:149], v[144:145], v[200:201]
	v_add_f32_e32 v163, v152, v153
	v_add_f32_dpp v154, v154, v154 quad_perm:[2,3,0,1] row_mask:0xf bank_mask:0xf bound_ctrl:1
	v_pk_fma_f32 v[146:147], v[240:241], v[196:197], v[146:147] op_sel:[0,0,0] op_sel_hi:[0,1,1]
	v_pk_fma_f32 v[148:149], v[240:241], v[204:205], v[148:149] op_sel:[0,0,0] op_sel_hi:[0,1,1]
	v_add_f32_dpp v180, v176, v178 quad_perm:[1,0,3,2] row_mask:0xf bank_mask:0xf
	v_add_f32_dpp v154, v154, v154 row_half_mirror row_mask:0xf bank_mask:0xf bound_ctrl:1
	ds_read_b128 v[126:129], v184 offset:23040
	ds_read_b128 v[130:133], v184 offset:23072
	v_add_f32_dpp v154, v154, v154 row_mirror row_mask:0xf bank_mask:0xf bound_ctrl:1
	ds_read_b128 v[134:137], v185 offset:23040
	v_pk_fma_f32 v[146:147], v[154:155], v[194:195], v[146:147] op_sel_hi:[0,1,1]
	v_pk_fma_f32 v[148:149], v[154:155], v[202:203], v[148:149] op_sel_hi:[0,1,1]
	ds_read_b128 v[222:225], v185 offset:23072
	ds_read_b128 v[236:239], v188 offset:23040
	ds_read2_b32 v[242:243], v227 offset0:160 offset1:176
	s_waitcnt lgkmcnt(6)
	v_pk_mul_f32 v[150:151], v[146:147], v[206:207]
	v_pk_fma_f32 v[150:151], v[148:149], v[214:215], v[150:151]
	v_pk_mul_f32 v[152:153], v[146:147], v[228:229]
	v_add_f32_e32 v154, v150, v151
	v_pk_fma_f32 v[152:153], v[148:149], v[230:231], v[152:153]
	v_pk_mul_f32 v[142:143], v[146:147], v[208:209]
	v_add_f32_dpp v154, v154, v154 quad_perm:[1,0,3,2] row_mask:0xf bank_mask:0xf bound_ctrl:1
	v_pk_mul_f32 v[144:145], v[148:149], v[216:217]
	v_add_f32_e32 v164, v152, v153
	v_add_f32_dpp v154, v154, v154 quad_perm:[2,3,0,1] row_mask:0xf bank_mask:0xf bound_ctrl:1
	v_pk_fma_f32 v[142:143], v[240:241], v[212:213], v[142:143] op_sel:[1,0,0] op_sel_hi:[1,1,1]
	v_pk_fma_f32 v[144:145], v[240:241], v[220:221], v[144:145] op_sel:[1,0,0] op_sel_hi:[1,1,1]
	v_add_f32_dpp v172, v156, v156 row_ror:8 row_mask:0xf bank_mask:0x3
	v_add_f32_dpp v154, v154, v154 row_half_mirror row_mask:0xf bank_mask:0xf bound_ctrl:1
	ds_read_b128 v[190:193], v184 offset:24576
	ds_read_b128 v[194:197], v184 offset:24608
	v_add_f32_dpp v173, v157, v157 row_ror:8 row_mask:0xf bank_mask:0x3
	v_add_f32_dpp v154, v154, v154 row_mirror row_mask:0xf bank_mask:0xf bound_ctrl:1
	v_pk_fma_f32 v[142:143], v[154:155], v[210:211], v[142:143] op_sel_hi:[0,1,1]
	v_pk_fma_f32 v[144:145], v[154:155], v[218:219], v[144:145] op_sel_hi:[0,1,1]
	v_add_f32_dpp v174, v158, v158 row_ror:8 row_mask:0xf bank_mask:0x3
	ds_read_b128 v[198:201], v185 offset:24576
	ds_read_b128 v[202:205], v185 offset:24608
	ds_read_b128 v[228:231], v188 offset:24576
	v_add_f32_dpp v175, v159, v159 row_ror:8 row_mask:0xf bank_mask:0x3
	s_waitcnt lgkmcnt(5)
; __device__ __forceinline__ void wkv_phase(const WkvT& W, unsigned char* lds) {
;     ...
;                 for (int t = 0; t < 32; ++t) {
;                     const f32x2 a2 = {nA[0], nA[1]}, w2 = {nA[2], nA[3]}, b2 = {nB[0], nB[1]}, k2 = {nB[2], nB[3]}, r2 = nr; const float v = nv;
;                     if (t + 1 < 32) { nA = *(const f32x4*)(pp + (t + 1) * 384); nB = *(const f32x4*)(pp + (t + 1) * 384 + 4); nr = *(const f32x2*)(pp + (t + 1) * 384 + 8); nv = pv[(t + 1) * 16]; }
;                     float S0 = S.x, S1 = S.y;
;                     float d = S0 * a2.x; d = __builtin_fmaf(S1, a2.y, d);
;                     float t0 = S0 * w2.x; t0 = __builtin_fmaf(v, k2.x, t0); asm volatile("" : "+v"(t0));
;                     float t1 = S1 * w2.y; t1 = __builtin_fmaf(v, k2.y, t1); asm volatile("" : "+v"(t1));
;                     float yprev; const float sa = wkv_reduce(d, ep, yprev);
;                     S0 = __builtin_fmaf(sa, b2.x, t0); asm volatile("" : "+v"(S0));
;                     S1 = __builtin_fmaf(sa, b2.y, t1); asm volatile("" : "+v"(S1));
;                     ep = S0 * r2.x; ep = __builtin_fmaf(S1, r2.y, ep);
;                     S.x = S0; S.y = S1;
;                     if (t >= 1) { const bool hit = oddrow && ((lane & 15) == ((t - 1) & 15)); if (t <= 16) yk0 = hit ? yprev : yk0; else yk1 = hit ? yprev : yk1; }
	v_pk_mul_f32 v[150:151], v[142:143], v[126:127]
	v_pk_fma_f32 v[150:151], v[144:145], v[134:135], v[150:151]
	v_pk_mul_f32 v[152:153], v[142:143], v[232:233]
	v_add_f32_e32 v154, v150, v151
	v_pk_fma_f32 v[152:153], v[144:145], v[234:235], v[152:153]
	v_pk_mul_f32 v[146:147], v[142:143], v[128:129]
	v_add_f32_dpp v154, v154, v154 quad_perm:[1,0,3,2] row_mask:0xf bank_mask:0xf bound_ctrl:1
	v_pk_mul_f32 v[148:149], v[144:145], v[136:137]
	v_add_f32_e32 v165, v152, v153
	v_add_f32_dpp v154, v154, v154 quad_perm:[2,3,0,1] row_mask:0xf bank_mask:0xf bound_ctrl:1
	v_pk_fma_f32 v[146:147], v[242:243], v[132:133], v[146:147] op_sel:[0,0,0] op_sel_hi:[0,1,1]
	v_pk_fma_f32 v[148:149], v[242:243], v[224:225], v[148:149] op_sel:[0,0,0] op_sel_hi:[0,1,1]
	v_add_f32_dpp v176, v160, v160 row_ror:8 row_mask:0xf bank_mask:0x3
	v_add_f32_dpp v154, v154, v154 row_half_mirror row_mask:0xf bank_mask:0xf bound_ctrl:1
	ds_read_b128 v[206:209], v184 offset:26112
	ds_read_b128 v[210:213], v184 offset:26144
	v_add_f32_dpp v177, v161, v161 row_ror:8 row_mask:0xf bank_mask:0x3
	v_add_f32_dpp v154, v154, v154 row_mirror row_mask:0xf bank_mask:0xf bound_ctrl:1
	ds_read_b128 v[214:217], v185 offset:26112
	v_pk_fma_f32 v[146:147], v[154:155], v[130:131], v[146:147] op_sel_hi:[0,1,1]
	v_pk_fma_f32 v[148:149], v[154:155], v[222:223], v[148:149] op_sel_hi:[0,1,1]
	v_add_f32_dpp v178, v162, v162 row_ror:8 row_mask:0xf bank_mask:0x3
	ds_read_b128 v[218:221], v185 offset:26144
	ds_read_b128 v[232:235], v188 offset:26112
	ds_read2_b32 v[240:241], v227 offset0:192 offset1:208
	v_add_f32_dpp v179, v163, v163 row_ror:8 row_mask:0xf bank_mask:0x3
	s_waitcnt lgkmcnt(6)
	v_pk_mul_f32 v[150:151], v[146:147], v[190:191]
	v_pk_fma_f32 v[150:151], v[148:149], v[198:199], v[150:151]
	v_pk_mul_f32 v[152:153], v[146:147], v[236:237]
	v_add_f32_e32 v154, v150, v151
	v_pk_fma_f32 v[152:153], v[148:149], v[238:239], v[152:153]
	v_pk_mul_f32 v[142:143], v[146:147], v[192:193]
	v_add_f32_dpp v154, v154, v154 quad_perm:[1,0,3,2] row_mask:0xf bank_mask:0xf bound_ctrl:1
	v_pk_mul_f32 v[144:145], v[148:149], v[200:201]
	v_add_f32_e32 v166, v152, v153
	v_add_f32_dpp v154, v154, v154 quad_perm:[2,3,0,1] row_mask:0xf bank_mask:0xf bound_ctrl:1
	v_pk_fma_f32 v[142:143], v[242:243], v[196:197], v[142:143] op_sel:[1,0,0] op_sel_hi:[1,1,1]
	v_pk_fma_f32 v[144:145], v[242:243], v[204:205], v[144:145] op_sel:[1,0,0] op_sel_hi:[1,1,1]
	v_add_f32_dpp v172, v164, v164 row_ror:8 row_mask:0xf bank_mask:0xc
	v_add_f32_dpp v154, v154, v154 row_half_mirror row_mask:0xf bank_mask:0xf bound_ctrl:1
	ds_read_b128 v[126:129], v184 offset:27648
	ds_read_b128 v[130:133], v184 offset:27680
	v_add_f32_dpp v154, v154, v154 row_mirror row_mask:0xf bank_mask:0xf bound_ctrl:1
	v_pk_fma_f32 v[142:143], v[154:155], v[194:195], v[142:143] op_sel_hi:[0,1,1]
	v_pk_fma_f32 v[144:145], v[154:155], v[202:203], v[144:145] op_sel_hi:[0,1,1]
	ds_read_b128 v[134:137], v185 offset:27648
	ds_read_b128 v[222:225], v185 offset:27680
	ds_read_b128 v[236:239], v188 offset:27648
	s_waitcnt lgkmcnt(5)
	v_pk_mul_f32 v[150:151], v[142:143], v[206:207]
	v_pk_fma_f32 v[150:151], v[144:145], v[214:215], v[150:151]
	v_pk_mul_f32 v[152:153], v[142:143], v[228:229]
	v_add_f32_e32 v154, v150, v151
	v_pk_fma_f32 v[152:153], v[144:145], v[230:231], v[152:153]
	v_pk_mul_f32 v[146:147], v[142:143], v[208:209]
	v_add_f32_dpp v154, v154, v154 quad_perm:[1,0,3,2] row_mask:0xf bank_mask:0xf bound_ctrl:1
	v_pk_mul_f32 v[148:149], v[144:145], v[216:217]
	v_add_f32_e32 v167, v152, v153
	v_add_f32_dpp v154, v154, v154 quad_perm:[2,3,0,1] row_mask:0xf bank_mask:0xf bound_ctrl:1
	v_pk_fma_f32 v[146:147], v[240:241], v[212:213], v[146:147] op_sel:[0,0,0] op_sel_hi:[0,1,1]
	v_pk_fma_f32 v[148:149], v[240:241], v[220:221], v[148:149] op_sel:[0,0,0] op_sel_hi:[0,1,1]
	v_add_f32_dpp v173, v165, v165 row_ror:8 row_mask:0xf bank_mask:0xc
	v_add_f32_dpp v154, v154, v154 row_half_mirror row_mask:0xf bank_mask:0xf bound_ctrl:1
	ds_read_b128 v[190:193], v184 offset:29184
	ds_read_b128 v[194:197], v184 offset:29216
	v_add_f32_dpp v154, v154, v154 row_mirror row_mask:0xf bank_mask:0xf bound_ctrl:1
	ds_read_b128 v[198:201], v185 offset:29184
	v_pk_fma_f32 v[146:147], v[154:155], v[210:211], v[146:147] op_sel_hi:[0,1,1]
	v_pk_fma_f32 v[148:149], v[154:155], v[218:219], v[148:149] op_sel_hi:[0,1,1]
	ds_read_b128 v[202:205], v185 offset:29216
	ds_read_b128 v[228:231], v188 offset:29184
	ds_read2_b32 v[242:243], v227 offset0:224 offset1:240
	s_waitcnt lgkmcnt(6)
; __device__ __forceinline__ void wkv_phase(const WkvT& W, unsigned char* lds) {
;     ...
;                 for (int t = 0; t < 32; ++t) {
;                     const f32x2 a2 = {nA[0], nA[1]}, w2 = {nA[2], nA[3]}, b2 = {nB[0], nB[1]}, k2 = {nB[2], nB[3]}, r2 = nr; const float v = nv;
;                     if (t + 1 < 32) { nA = *(const f32x4*)(pp + (t + 1) * 384); nB = *(const f32x4*)(pp + (t + 1) * 384 + 4); nr = *(const f32x2*)(pp + (t + 1) * 384 + 8); nv = pv[(t + 1) * 16]; }
;                     float S0 = S.x, S1 = S.y;
;                     float d = S0 * a2.x; d = __builtin_fmaf(S1, a2.y, d);
;                     float t0 = S0 * w2.x; t0 = __builtin_fmaf(v, k2.x, t0); asm volatile("" : "+v"(t0));
;                     float t1 = S1 * w2.y; t1 = __builtin_fmaf(v, k2.y, t1); asm volatile("" : "+v"(t1));
;                     float yprev; const float sa = wkv_reduce(d, ep, yprev);
;                     S0 = __builtin_fmaf(sa, b2.x, t0); asm volatile("" : "+v"(S0));
;                     S1 = __builtin_fmaf(sa, b2.y, t1); asm volatile("" : "+v"(S1));
;                     ep = S0 * r2.x; ep = __builtin_fmaf(S1, r2.y, ep);
;                     S.x = S0; S.y = S1;
;                     if (t >= 1) { const bool hit = oddrow && ((lane & 15) == ((t - 1) & 15)); if (t <= 16) yk0 = hit ? yprev : yk0; else yk1 = hit ? yprev : yk1; }
;                 }
;                 { float ylast; (void)wkv_reduce(0.f, ep, ylast); yk1 = (oddrow && (lane & 15) == 15) ? ylast : yk1; }
;                 if (oddrow) { sY[bi * 512 + (lane & 15) * 16 + il] = yk0; sY[bi * 512 + (16 + (lane & 15)) * 16 + il] = yk1; }
	v_pk_mul_f32 v[150:151], v[146:147], v[126:127]
	v_pk_fma_f32 v[150:151], v[148:149], v[134:135], v[150:151]
	v_pk_mul_f32 v[152:153], v[146:147], v[232:233]
	v_add_f32_e32 v154, v150, v151
	v_pk_fma_f32 v[152:153], v[148:149], v[234:235], v[152:153]
	v_pk_mul_f32 v[142:143], v[146:147], v[128:129]
	v_add_f32_dpp v154, v154, v154 quad_perm:[1,0,3,2] row_mask:0xf bank_mask:0xf bound_ctrl:1
	v_pk_mul_f32 v[144:145], v[148:149], v[136:137]
	v_add_f32_e32 v168, v152, v153
	v_add_f32_dpp v154, v154, v154 quad_perm:[2,3,0,1] row_mask:0xf bank_mask:0xf bound_ctrl:1
	v_pk_fma_f32 v[142:143], v[240:241], v[132:133], v[142:143] op_sel:[1,0,0] op_sel_hi:[1,1,1]
	v_pk_fma_f32 v[144:145], v[240:241], v[224:225], v[144:145] op_sel:[1,0,0] op_sel_hi:[1,1,1]
	v_add_f32_dpp v174, v166, v166 row_ror:8 row_mask:0xf bank_mask:0xc
	v_add_f32_dpp v154, v154, v154 row_half_mirror row_mask:0xf bank_mask:0xf bound_ctrl:1
	ds_read_b128 v[206:209], v184 offset:30720
	ds_read_b128 v[210:213], v184 offset:30752
	v_add_f32_dpp v154, v154, v154 row_mirror row_mask:0xf bank_mask:0xf bound_ctrl:1
	v_pk_fma_f32 v[142:143], v[154:155], v[130:131], v[142:143] op_sel_hi:[0,1,1]
	v_pk_fma_f32 v[144:145], v[154:155], v[222:223], v[144:145] op_sel_hi:[0,1,1]
	ds_read_b128 v[214:217], v185 offset:30720
	ds_read_b128 v[218:221], v185 offset:30752
	ds_read_b128 v[232:235], v188 offset:30720
	s_waitcnt lgkmcnt(5)
	v_pk_mul_f32 v[150:151], v[142:143], v[190:191]
	v_pk_fma_f32 v[150:151], v[144:145], v[198:199], v[150:151]
	v_pk_mul_f32 v[152:153], v[142:143], v[236:237]
	v_add_f32_e32 v154, v150, v151
	v_pk_fma_f32 v[152:153], v[144:145], v[238:239], v[152:153]
	v_pk_mul_f32 v[146:147], v[142:143], v[192:193]
	v_add_f32_dpp v154, v154, v154 quad_perm:[1,0,3,2] row_mask:0xf bank_mask:0xf bound_ctrl:1
	v_pk_mul_f32 v[148:149], v[144:145], v[200:201]
	v_add_f32_e32 v169, v152, v153
	v_add_f32_dpp v154, v154, v154 quad_perm:[2,3,0,1] row_mask:0xf bank_mask:0xf bound_ctrl:1
	v_pk_fma_f32 v[146:147], v[242:243], v[196:197], v[146:147] op_sel:[0,0,0] op_sel_hi:[0,1,1]
	v_pk_fma_f32 v[148:149], v[242:243], v[204:205], v[148:149] op_sel:[0,0,0] op_sel_hi:[0,1,1]
	v_add_f32_dpp v175, v167, v167 row_ror:8 row_mask:0xf bank_mask:0xc
	v_add_f32_dpp v154, v154, v154 row_half_mirror row_mask:0xf bank_mask:0xf bound_ctrl:1
	s_nop 1
	v_add_f32_dpp v154, v154, v154 row_mirror row_mask:0xf bank_mask:0xf bound_ctrl:1
	v_pk_fma_f32 v[146:147], v[154:155], v[194:195], v[146:147] op_sel_hi:[0,1,1]
	v_pk_fma_f32 v[148:149], v[154:155], v[202:203], v[148:149] op_sel_hi:[0,1,1]
	s_waitcnt lgkmcnt(0)
	v_pk_mul_f32 v[150:151], v[146:147], v[206:207]
	v_pk_fma_f32 v[150:151], v[148:149], v[214:215], v[150:151]
	v_pk_mul_f32 v[152:153], v[146:147], v[228:229]
	v_add_f32_e32 v154, v150, v151
	v_pk_fma_f32 v[152:153], v[148:149], v[230:231], v[152:153]
	v_pk_mul_f32 v[142:143], v[146:147], v[208:209]
	v_add_f32_dpp v154, v154, v154 quad_perm:[1,0,3,2] row_mask:0xf bank_mask:0xf bound_ctrl:1
	v_pk_mul_f32 v[144:145], v[148:149], v[216:217]
	v_add_f32_e32 v170, v152, v153
	v_add_f32_dpp v154, v154, v154 quad_perm:[2,3,0,1] row_mask:0xf bank_mask:0xf bound_ctrl:1
	v_pk_fma_f32 v[142:143], v[242:243], v[212:213], v[142:143] op_sel:[1,0,0] op_sel_hi:[1,1,1]
	v_pk_fma_f32 v[144:145], v[242:243], v[220:221], v[144:145] op_sel:[1,0,0] op_sel_hi:[1,1,1]
	v_add_f32_dpp v176, v168, v168 row_ror:8 row_mask:0xf bank_mask:0xc
	v_add_f32_dpp v154, v154, v154 row_half_mirror row_mask:0xf bank_mask:0xf bound_ctrl:1
	s_nop 1
	v_add_f32_dpp v177, v169, v169 row_ror:8 row_mask:0xf bank_mask:0xc
	v_add_f32_dpp v154, v154, v154 row_mirror row_mask:0xf bank_mask:0xf bound_ctrl:1
	v_pk_fma_f32 v[142:143], v[154:155], v[210:211], v[142:143] op_sel_hi:[0,1,1]
	v_pk_fma_f32 v[144:145], v[154:155], v[218:219], v[144:145] op_sel_hi:[0,1,1]
	v_pk_mul_f32 v[152:153], v[142:143], v[232:233]
	v_pk_fma_f32 v[152:153], v[144:145], v[234:235], v[152:153]
	s_nop 0
	v_add_f32_e32 v171, v152, v153
	v_add_f32_dpp v178, v170, v170 row_ror:8 row_mask:0xf bank_mask:0xc
	s_nop 0
	v_add_f32_dpp v179, v171, v171 row_ror:8 row_mask:0xf bank_mask:0xc
	s_nop 0
	v_add_f32_dpp v56, v172, v172 row_half_mirror row_mask:0xf bank_mask:0x5
	v_add_f32_dpp v57, v173, v173 row_half_mirror row_mask:0xf bank_mask:0x5
	v_add_f32_dpp v58, v174, v174 row_half_mirror row_mask:0xf bank_mask:0x5
	v_add_f32_dpp v59, v175, v175 row_half_mirror row_mask:0xf bank_mask:0x5
	v_add_f32_dpp v56, v176, v176 row_half_mirror row_mask:0xf bank_mask:0xa
	v_add_f32_dpp v57, v177, v177 row_half_mirror row_mask:0xf bank_mask:0xa
	v_add_f32_dpp v58, v178, v178 row_half_mirror row_mask:0xf bank_mask:0xa
	v_add_f32_dpp v59, v179, v179 row_half_mirror row_mask:0xf bank_mask:0xa
	v_cndmask_b32_e64 v178, v56, v58, s[14:15]
	v_cndmask_b32_e64 v176, v58, v56, s[14:15]
	v_cndmask_b32_e64 v179, v57, v59, s[14:15]
	v_cndmask_b32_e64 v177, v59, v57, s[14:15]
	s_nop 1
	v_add_f32_dpp v172, v176, v178 quad_perm:[2,3,0,1] row_mask:0xf bank_mask:0xf
	v_add_f32_dpp v173, v177, v179 quad_perm:[2,3,0,1] row_mask:0xf bank_mask:0xf
	v_cndmask_b32_e64 v176, v173, v172, s[16:17]
	v_cndmask_b32_e64 v178, v172, v173, s[16:17]
	s_nop 1
	v_add_f32_dpp v181, v176, v178 quad_perm:[1,0,3,2] row_mask:0xf bank_mask:0xf
	ds_write2st64_b32 v187, v180, v181 offset0:8 offset1:12
